# noprio + LDS-DMA loads interleaved among the ds_reads of each load segment (no s_nop between m0 write and DMA)
# speedup vs baseline: 1.0150x; 1.0020x over previous
.LBB0_140:
	s_add_u32 s2, s22, 0xfff80080
	s_addc_u32 s20, s23, -1
	s_add_i32 s45, 0, 0x10000
	s_cmp_eq_u32 s44, 28
	s_cselect_b32 s25, s15, s20
	s_cselect_b32 s24, s40, s2
	v_add_u32_e32 v144, s45, v148
	s_cselect_b32 s21, s13, s43
	s_cselect_b32 s20, s41, s42
	s_add_u32 s100, s22, 0xfff80000
	s_addc_u32 s101, s23, -1
	s_add_i32 s2, 0, 0x14000
	s_mov_b32 m0, s35
	ds_read_b128 v[140:143], v144
	ds_read_b128 v[152:155], v144 offset:1024
	ds_read_b128 v[156:159], v144 offset:2048
	ds_read_b128 v[160:163], v144 offset:3072
	global_load_lds_dwordx4 v136, s[100:101]
	s_mov_b32 m0, s36
	v_add_u32_e32 v144, s2, v148
	ds_read_b128 v[164:167], v144
	ds_read_b128 v[168:171], v144 offset:1024
	ds_read_b128 v[172:175], v144 offset:2048
	ds_read_b128 v[176:179], v144 offset:3072
	global_load_lds_dwordx4 v138, s[100:101]
	s_add_i32 m0, s29, 0xc000
	ds_read_b128 v[180:183], v151
	ds_read_b128 v[184:187], v151 offset:1024
	ds_read_b128 v[188:191], v151 offset:2048
	ds_read_b128 v[192:195], v151 offset:3072
	global_load_lds_dwordx4 v136, s[22:23]
	s_add_i32 m0, s29, 0xe000
	ds_read_b128 v[206:209], v151 offset:4096
	ds_read_b128 v[210:213], v151 offset:5120
	ds_read_b128 v[214:217], v151 offset:6144
	ds_read_b128 v[218:221], v151 offset:7168
	global_load_lds_dwordx4 v138, s[22:23]
	s_waitcnt vmcnt(8)
	s_waitcnt lgkmcnt(0)
	s_barrier
	s_waitcnt lgkmcnt(0)
	v_mfma_f32_16x16x32_bf16 v[126:129], v[140:143], v[180:183], v[126:129]
	v_mfma_f32_16x16x32_bf16 v[122:125], v[156:159], v[180:183], v[122:125]
	v_mfma_f32_16x16x32_bf16 v[110:113], v[140:143], v[188:191], v[110:113]
	v_mfma_f32_16x16x32_bf16 v[106:109], v[156:159], v[188:191], v[106:109]
	v_mfma_f32_16x16x32_bf16 v[94:97], v[140:143], v[206:209], v[94:97]
	v_mfma_f32_16x16x32_bf16 v[90:93], v[156:159], v[206:209], v[90:93]
	v_mfma_f32_16x16x32_bf16 v[78:81], v[140:143], v[214:217], v[78:81]
	v_mfma_f32_16x16x32_bf16 v[74:77], v[156:159], v[214:217], v[74:77]
	v_mfma_f32_16x16x32_bf16 v[126:129], v[152:155], v[184:187], v[126:129]
	v_mfma_f32_16x16x32_bf16 v[122:125], v[160:163], v[184:187], v[122:125]
	v_mfma_f32_16x16x32_bf16 v[110:113], v[152:155], v[192:195], v[110:113]
	v_mfma_f32_16x16x32_bf16 v[106:109], v[160:163], v[192:195], v[106:109]
	v_mfma_f32_16x16x32_bf16 v[94:97], v[152:155], v[210:213], v[94:97]
	v_mfma_f32_16x16x32_bf16 v[90:93], v[160:163], v[210:213], v[90:93]
	v_mfma_f32_16x16x32_bf16 v[78:81], v[152:155], v[218:221], v[78:81]
	v_mfma_f32_16x16x32_bf16 v[74:77], v[160:163], v[218:221], v[74:77]
	v_mfma_f32_16x16x32_bf16 v[118:121], v[164:167], v[180:183], v[118:121]
	v_mfma_f32_16x16x32_bf16 v[114:117], v[172:175], v[180:183], v[114:117]
	v_mfma_f32_16x16x32_bf16 v[102:105], v[164:167], v[188:191], v[102:105]
	v_mfma_f32_16x16x32_bf16 v[98:101], v[172:175], v[188:191], v[98:101]
	v_mfma_f32_16x16x32_bf16 v[86:89], v[164:167], v[206:209], v[86:89]
	v_mfma_f32_16x16x32_bf16 v[82:85], v[172:175], v[206:209], v[82:85]
	v_mfma_f32_16x16x32_bf16 v[70:73], v[164:167], v[214:217], v[70:73]
	v_mfma_f32_16x16x32_bf16 v[66:69], v[172:175], v[214:217], v[66:69]
	v_mfma_f32_16x16x32_bf16 v[118:121], v[168:171], v[184:187], v[118:121]
	v_mfma_f32_16x16x32_bf16 v[114:117], v[176:179], v[184:187], v[114:117]
	v_mfma_f32_16x16x32_bf16 v[102:105], v[168:171], v[192:195], v[102:105]
	v_mfma_f32_16x16x32_bf16 v[98:101], v[176:179], v[192:195], v[98:101]
	v_mfma_f32_16x16x32_bf16 v[86:89], v[168:171], v[210:213], v[86:89]
	v_mfma_f32_16x16x32_bf16 v[82:85], v[176:179], v[210:213], v[82:85]
	v_mfma_f32_16x16x32_bf16 v[70:73], v[168:171], v[218:221], v[70:73]
	v_mfma_f32_16x16x32_bf16 v[66:69], v[176:179], v[218:221], v[66:69]
	s_barrier
	s_add_u32 s46, s20, 0x80000
	s_addc_u32 s47, s21, 0
	s_add_i32 s45, s45, s28
	s_mov_b32 m0, s45
	ds_read_b128 v[180:183], v151 offset:16384
	ds_read_b128 v[184:187], v151 offset:17408
	global_load_lds_dwordx4 v0, s[20:21]
	s_add_i32 m0, s45, 0x2000
	s_add_i32 s2, s2, s28
	ds_read_b128 v[188:191], v151 offset:18432
	ds_read_b128 v[192:195], v151 offset:19456
	global_load_lds_dwordx4 v130, s[20:21]
	s_mov_b32 m0, s2
	ds_read_b128 v[206:209], v151 offset:20480
	ds_read_b128 v[210:213], v151 offset:21504
	global_load_lds_dwordx4 v0, s[46:47]
	s_add_i32 m0, s2, 0x2000
	ds_read_b128 v[214:217], v151 offset:22528
	ds_read_b128 v[218:221], v151 offset:23552
	global_load_lds_dwordx4 v130, s[46:47]
	s_waitcnt vmcnt(6)
	s_waitcnt lgkmcnt(0)
	s_barrier
	s_waitcnt lgkmcnt(0)
	v_mfma_f32_16x16x32_bf16 v[62:65], v[140:143], v[180:183], v[62:65]
	v_mfma_f32_16x16x32_bf16 v[58:61], v[156:159], v[180:183], v[58:61]
	v_mfma_f32_16x16x32_bf16 v[46:49], v[140:143], v[188:191], v[46:49]
	v_mfma_f32_16x16x32_bf16 v[42:45], v[156:159], v[188:191], v[42:45]
	v_mfma_f32_16x16x32_bf16 v[30:33], v[140:143], v[206:209], v[30:33]
	v_mfma_f32_16x16x32_bf16 v[26:29], v[156:159], v[206:209], v[26:29]
	v_mfma_f32_16x16x32_bf16 v[14:17], v[140:143], v[214:217], v[14:17]
	v_mfma_f32_16x16x32_bf16 v[10:13], v[156:159], v[214:217], v[10:13]
	v_mfma_f32_16x16x32_bf16 v[62:65], v[152:155], v[184:187], v[62:65]
	v_mfma_f32_16x16x32_bf16 v[58:61], v[160:163], v[184:187], v[58:61]
	v_mfma_f32_16x16x32_bf16 v[46:49], v[152:155], v[192:195], v[46:49]
	v_mfma_f32_16x16x32_bf16 v[42:45], v[160:163], v[192:195], v[42:45]
	v_mfma_f32_16x16x32_bf16 v[30:33], v[152:155], v[210:213], v[30:33]
	v_mfma_f32_16x16x32_bf16 v[26:29], v[160:163], v[210:213], v[26:29]
	v_mfma_f32_16x16x32_bf16 v[14:17], v[152:155], v[218:221], v[14:17]
	v_mfma_f32_16x16x32_bf16 v[10:13], v[160:163], v[218:221], v[10:13]
	v_mfma_f32_16x16x32_bf16 v[54:57], v[164:167], v[180:183], v[54:57]
	v_mfma_f32_16x16x32_bf16 v[50:53], v[172:175], v[180:183], v[50:53]
	v_mfma_f32_16x16x32_bf16 v[38:41], v[164:167], v[188:191], v[38:41]
	v_mfma_f32_16x16x32_bf16 v[34:37], v[172:175], v[188:191], v[34:37]
	v_mfma_f32_16x16x32_bf16 v[22:25], v[164:167], v[206:209], v[22:25]
	v_mfma_f32_16x16x32_bf16 v[18:21], v[172:175], v[206:209], v[18:21]
	v_mfma_f32_16x16x32_bf16 v[6:9], v[164:167], v[214:217], v[6:9]
	v_mfma_f32_16x16x32_bf16 v[2:5], v[172:175], v[214:217], v[2:5]
	v_mfma_f32_16x16x32_bf16 v[54:57], v[168:171], v[184:187], v[54:57]
	v_mfma_f32_16x16x32_bf16 v[50:53], v[176:179], v[184:187], v[50:53]
	v_mfma_f32_16x16x32_bf16 v[38:41], v[168:171], v[192:195], v[38:41]
	v_mfma_f32_16x16x32_bf16 v[34:37], v[176:179], v[192:195], v[34:37]
	v_mfma_f32_16x16x32_bf16 v[22:25], v[168:171], v[210:213], v[22:25]
	v_mfma_f32_16x16x32_bf16 v[18:21], v[176:179], v[210:213], v[18:21]
	v_mfma_f32_16x16x32_bf16 v[6:9], v[168:171], v[218:221], v[6:9]
	v_mfma_f32_16x16x32_bf16 v[2:5], v[176:179], v[218:221], v[2:5]
	s_barrier
	s_add_u32 s24, s24, 0x80000
	s_addc_u32 s25, s25, 0
	s_add_u32 s100, s24, 0xfff80000
	s_addc_u32 s101, s25, -1
	s_add_i32 s2, 0, 0x18000
	s_add_i32 s45, 0, 0x1c000
	v_add_u32_e32 v160, s2, v148
	v_add_u32_e32 v176, s45, v148
	s_mov_b32 m0, s29
	ds_read_b128 v[140:143], v160
	ds_read_b128 v[152:155], v160 offset:1024
	ds_read_b128 v[156:159], v160 offset:2048
	ds_read_b128 v[160:163], v160 offset:3072
	global_load_lds_dwordx4 v134, s[100:101]
	s_mov_b32 m0, s30
	ds_read_b128 v[164:167], v176
	ds_read_b128 v[168:171], v176 offset:1024
	ds_read_b128 v[172:175], v176 offset:2048
	ds_read_b128 v[176:179], v176 offset:3072
	global_load_lds_dwordx4 v132, s[100:101]
	s_mov_b32 m0, s31
	ds_read_b128 v[180:183], v151 offset:32768
	ds_read_b128 v[184:187], v151 offset:33792
	ds_read_b128 v[188:191], v151 offset:34816
	ds_read_b128 v[192:195], v151 offset:35840
	global_load_lds_dwordx4 v134, s[24:25]
	s_mov_b32 m0, s33
	ds_read_b128 v[206:209], v151 offset:36864
	ds_read_b128 v[210:213], v151 offset:37888
	ds_read_b128 v[214:217], v151 offset:38912
	ds_read_b128 v[218:221], v151 offset:39936
	global_load_lds_dwordx4 v132, s[24:25]
	s_waitcnt vmcnt(8)
	s_waitcnt lgkmcnt(0)
	s_barrier
	s_waitcnt lgkmcnt(0)
	v_mfma_f32_16x16x32_bf16 v[126:129], v[140:143], v[180:183], v[126:129]
	v_mfma_f32_16x16x32_bf16 v[122:125], v[156:159], v[180:183], v[122:125]
	v_mfma_f32_16x16x32_bf16 v[110:113], v[140:143], v[188:191], v[110:113]
	v_mfma_f32_16x16x32_bf16 v[106:109], v[156:159], v[188:191], v[106:109]
	v_mfma_f32_16x16x32_bf16 v[94:97], v[140:143], v[206:209], v[94:97]
	v_mfma_f32_16x16x32_bf16 v[90:93], v[156:159], v[206:209], v[90:93]
	v_mfma_f32_16x16x32_bf16 v[78:81], v[140:143], v[214:217], v[78:81]
	v_mfma_f32_16x16x32_bf16 v[74:77], v[156:159], v[214:217], v[74:77]
	v_mfma_f32_16x16x32_bf16 v[126:129], v[152:155], v[184:187], v[126:129]
	v_mfma_f32_16x16x32_bf16 v[122:125], v[160:163], v[184:187], v[122:125]
	v_mfma_f32_16x16x32_bf16 v[110:113], v[152:155], v[192:195], v[110:113]
	v_mfma_f32_16x16x32_bf16 v[106:109], v[160:163], v[192:195], v[106:109]
	v_mfma_f32_16x16x32_bf16 v[94:97], v[152:155], v[210:213], v[94:97]
	v_mfma_f32_16x16x32_bf16 v[90:93], v[160:163], v[210:213], v[90:93]
	v_mfma_f32_16x16x32_bf16 v[78:81], v[152:155], v[218:221], v[78:81]
	v_mfma_f32_16x16x32_bf16 v[74:77], v[160:163], v[218:221], v[74:77]
	v_mfma_f32_16x16x32_bf16 v[118:121], v[164:167], v[180:183], v[118:121]
	v_mfma_f32_16x16x32_bf16 v[114:117], v[172:175], v[180:183], v[114:117]
	v_mfma_f32_16x16x32_bf16 v[102:105], v[164:167], v[188:191], v[102:105]
	v_mfma_f32_16x16x32_bf16 v[98:101], v[172:175], v[188:191], v[98:101]
	v_mfma_f32_16x16x32_bf16 v[86:89], v[164:167], v[206:209], v[86:89]
	v_mfma_f32_16x16x32_bf16 v[82:85], v[172:175], v[206:209], v[82:85]
	v_mfma_f32_16x16x32_bf16 v[70:73], v[164:167], v[214:217], v[70:73]
	v_mfma_f32_16x16x32_bf16 v[66:69], v[172:175], v[214:217], v[66:69]
	v_mfma_f32_16x16x32_bf16 v[118:121], v[168:171], v[184:187], v[118:121]
	v_mfma_f32_16x16x32_bf16 v[114:117], v[176:179], v[184:187], v[114:117]
	v_mfma_f32_16x16x32_bf16 v[102:105], v[168:171], v[192:195], v[102:105]
	v_mfma_f32_16x16x32_bf16 v[98:101], v[176:179], v[192:195], v[98:101]
	v_mfma_f32_16x16x32_bf16 v[86:89], v[168:171], v[210:213], v[86:89]
	v_mfma_f32_16x16x32_bf16 v[82:85], v[176:179], v[210:213], v[82:85]
	v_mfma_f32_16x16x32_bf16 v[70:73], v[168:171], v[218:221], v[70:73]
	v_mfma_f32_16x16x32_bf16 v[66:69], v[176:179], v[218:221], v[66:69]
	s_barrier
	s_add_u32 s20, s20, 0x80080
	s_addc_u32 s21, s21, 0
	s_add_u32 s46, s46, 0xfff80080
	s_addc_u32 s47, s47, -1
	s_add_i32 s2, s2, s28
	s_mov_b32 m0, s2
	ds_read_b128 v[180:183], v151 offset:49152
	ds_read_b128 v[184:187], v151 offset:50176
	global_load_lds_dwordx4 v0, s[46:47]
	s_add_i32 m0, s2, 0x2000
	s_add_i32 s2, s45, s28
	ds_read_b128 v[188:191], v151 offset:51200
	ds_read_b128 v[192:195], v151 offset:52224
	global_load_lds_dwordx4 v130, s[46:47]
	s_mov_b32 m0, s2
	ds_read_b128 v[206:209], v151 offset:53248
	ds_read_b128 v[210:213], v151 offset:54272
	global_load_lds_dwordx4 v0, s[20:21]
	s_add_i32 m0, s2, 0x2000
	ds_read_b128 v[214:217], v151 offset:55296
	ds_read_b128 v[218:221], v151 offset:56320
	global_load_lds_dwordx4 v130, s[20:21]
	s_waitcnt vmcnt(6)
	s_waitcnt lgkmcnt(0)
	s_barrier
	s_waitcnt lgkmcnt(0)
	v_mfma_f32_16x16x32_bf16 v[62:65], v[140:143], v[180:183], v[62:65]
	v_mfma_f32_16x16x32_bf16 v[58:61], v[156:159], v[180:183], v[58:61]
	v_mfma_f32_16x16x32_bf16 v[46:49], v[140:143], v[188:191], v[46:49]
	v_mfma_f32_16x16x32_bf16 v[42:45], v[156:159], v[188:191], v[42:45]
	v_mfma_f32_16x16x32_bf16 v[30:33], v[140:143], v[206:209], v[30:33]
	v_mfma_f32_16x16x32_bf16 v[26:29], v[156:159], v[206:209], v[26:29]
	v_mfma_f32_16x16x32_bf16 v[14:17], v[140:143], v[214:217], v[14:17]
	v_mfma_f32_16x16x32_bf16 v[10:13], v[156:159], v[214:217], v[10:13]
	v_mfma_f32_16x16x32_bf16 v[62:65], v[152:155], v[184:187], v[62:65]
	v_mfma_f32_16x16x32_bf16 v[58:61], v[160:163], v[184:187], v[58:61]
	v_mfma_f32_16x16x32_bf16 v[46:49], v[152:155], v[192:195], v[46:49]
	v_mfma_f32_16x16x32_bf16 v[42:45], v[160:163], v[192:195], v[42:45]
	v_mfma_f32_16x16x32_bf16 v[30:33], v[152:155], v[210:213], v[30:33]
	v_mfma_f32_16x16x32_bf16 v[26:29], v[160:163], v[210:213], v[26:29]
	v_mfma_f32_16x16x32_bf16 v[14:17], v[152:155], v[218:221], v[14:17]
	v_mfma_f32_16x16x32_bf16 v[10:13], v[160:163], v[218:221], v[10:13]
	v_mfma_f32_16x16x32_bf16 v[54:57], v[164:167], v[180:183], v[54:57]
	v_mfma_f32_16x16x32_bf16 v[50:53], v[172:175], v[180:183], v[50:53]
	v_mfma_f32_16x16x32_bf16 v[38:41], v[164:167], v[188:191], v[38:41]
	v_mfma_f32_16x16x32_bf16 v[34:37], v[172:175], v[188:191], v[34:37]
	v_mfma_f32_16x16x32_bf16 v[22:25], v[164:167], v[206:209], v[22:25]
	v_mfma_f32_16x16x32_bf16 v[18:21], v[172:175], v[206:209], v[18:21]
	v_mfma_f32_16x16x32_bf16 v[6:9], v[164:167], v[214:217], v[6:9]
	v_mfma_f32_16x16x32_bf16 v[2:5], v[172:175], v[214:217], v[2:5]
	v_mfma_f32_16x16x32_bf16 v[54:57], v[168:171], v[184:187], v[54:57]
	v_mfma_f32_16x16x32_bf16 v[50:53], v[176:179], v[184:187], v[50:53]
	v_mfma_f32_16x16x32_bf16 v[38:41], v[168:171], v[192:195], v[38:41]
	v_mfma_f32_16x16x32_bf16 v[34:37], v[176:179], v[192:195], v[34:37]
	v_mfma_f32_16x16x32_bf16 v[22:25], v[168:171], v[210:213], v[22:25]
	v_mfma_f32_16x16x32_bf16 v[18:21], v[176:179], v[210:213], v[18:21]
	v_mfma_f32_16x16x32_bf16 v[6:9], v[168:171], v[218:221], v[6:9]
	v_mfma_f32_16x16x32_bf16 v[2:5], v[176:179], v[218:221], v[2:5]
	s_barrier
	s_add_i32 s44, s44, 2
	s_add_u32 s22, s22, 0x100
	s_addc_u32 s23, s23, 0
	s_add_u32 s42, s42, 0x100
	s_addc_u32 s43, s43, 0
	s_cmp_gt_u32 s44, 29
	s_cbranch_scc0 .LBB0_140
	s_and_b64 vcc, exec, s[10:11]
	s_cbranch_vccz .LBB0_143
	s_barrier

.LBB0_168:
	s_add_u32 s2, s26, 0xfff80080
	s_addc_u32 s24, s27, -1
	s_add_i32 s50, 0, 0x10000
	s_cmp_eq_u32 s49, 28
	s_cselect_b32 s29, s19, s24
	s_cselect_b32 s28, s44, s2
	v_add_u32_e32 v144, s50, v152
	s_cselect_b32 s25, s17, s47
	s_cselect_b32 s24, s45, s46
	s_add_u32 s100, s26, 0xfff80000
	s_addc_u32 s101, s27, -1
	s_add_i32 s2, 0, 0x14000
	s_mov_b32 m0, s39
	ds_read_b128 v[140:143], v144
	ds_read_b128 v[148:151], v144 offset:1024
	ds_read_b128 v[156:159], v144 offset:2048
	ds_read_b128 v[160:163], v144 offset:3072
	global_load_lds_dwordx4 v136, s[100:101]
	s_mov_b32 m0, s40
	v_add_u32_e32 v144, s2, v152
	ds_read_b128 v[164:167], v144
	ds_read_b128 v[168:171], v144 offset:1024
	ds_read_b128 v[172:175], v144 offset:2048
	ds_read_b128 v[176:179], v144 offset:3072
	global_load_lds_dwordx4 v138, s[100:101]
	s_add_i32 m0, s33, 0xc000
	ds_read_b128 v[180:183], v155
	ds_read_b128 v[184:187], v155 offset:1024
	ds_read_b128 v[188:191], v155 offset:2048
	ds_read_b128 v[192:195], v155 offset:3072
	global_load_lds_dwordx4 v136, s[26:27]
	s_add_i32 m0, s33, 0xe000
	ds_read_b128 v[206:209], v155 offset:4096
	ds_read_b128 v[210:213], v155 offset:5120
	ds_read_b128 v[214:217], v155 offset:6144
	ds_read_b128 v[218:221], v155 offset:7168
	global_load_lds_dwordx4 v138, s[26:27]
	s_waitcnt vmcnt(8)
	s_waitcnt lgkmcnt(0)
	s_barrier
	s_waitcnt lgkmcnt(0)
	v_mfma_f32_16x16x32_bf16 v[122:125], v[140:143], v[180:183], v[122:125]
	v_mfma_f32_16x16x32_bf16 v[114:117], v[156:159], v[180:183], v[114:117]
	v_mfma_f32_16x16x32_bf16 v[106:109], v[140:143], v[188:191], v[106:109]
	v_mfma_f32_16x16x32_bf16 v[98:101], v[156:159], v[188:191], v[98:101]
	v_mfma_f32_16x16x32_bf16 v[90:93], v[140:143], v[206:209], v[90:93]
	v_mfma_f32_16x16x32_bf16 v[82:85], v[156:159], v[206:209], v[82:85]
	v_mfma_f32_16x16x32_bf16 v[74:77], v[140:143], v[214:217], v[74:77]
	v_mfma_f32_16x16x32_bf16 v[66:69], v[156:159], v[214:217], v[66:69]
	v_mfma_f32_16x16x32_bf16 v[122:125], v[148:151], v[184:187], v[122:125]
	v_mfma_f32_16x16x32_bf16 v[114:117], v[160:163], v[184:187], v[114:117]
	v_mfma_f32_16x16x32_bf16 v[106:109], v[148:151], v[192:195], v[106:109]
	v_mfma_f32_16x16x32_bf16 v[98:101], v[160:163], v[192:195], v[98:101]
	v_mfma_f32_16x16x32_bf16 v[90:93], v[148:151], v[210:213], v[90:93]
	v_mfma_f32_16x16x32_bf16 v[82:85], v[160:163], v[210:213], v[82:85]
	v_mfma_f32_16x16x32_bf16 v[74:77], v[148:151], v[218:221], v[74:77]
	v_mfma_f32_16x16x32_bf16 v[66:69], v[160:163], v[218:221], v[66:69]
	v_mfma_f32_16x16x32_bf16 v[126:129], v[164:167], v[180:183], v[126:129]
	v_mfma_f32_16x16x32_bf16 v[118:121], v[172:175], v[180:183], v[118:121]
	v_mfma_f32_16x16x32_bf16 v[110:113], v[164:167], v[188:191], v[110:113]
	v_mfma_f32_16x16x32_bf16 v[102:105], v[172:175], v[188:191], v[102:105]
	v_mfma_f32_16x16x32_bf16 v[94:97], v[164:167], v[206:209], v[94:97]
	v_mfma_f32_16x16x32_bf16 v[86:89], v[172:175], v[206:209], v[86:89]
	v_mfma_f32_16x16x32_bf16 v[78:81], v[164:167], v[214:217], v[78:81]
	v_mfma_f32_16x16x32_bf16 v[70:73], v[172:175], v[214:217], v[70:73]
	v_mfma_f32_16x16x32_bf16 v[126:129], v[168:171], v[184:187], v[126:129]
	v_mfma_f32_16x16x32_bf16 v[118:121], v[176:179], v[184:187], v[118:121]
	v_mfma_f32_16x16x32_bf16 v[110:113], v[168:171], v[192:195], v[110:113]
	v_mfma_f32_16x16x32_bf16 v[102:105], v[176:179], v[192:195], v[102:105]
	v_mfma_f32_16x16x32_bf16 v[94:97], v[168:171], v[210:213], v[94:97]
	v_mfma_f32_16x16x32_bf16 v[86:89], v[176:179], v[210:213], v[86:89]
	v_mfma_f32_16x16x32_bf16 v[78:81], v[168:171], v[218:221], v[78:81]
	v_mfma_f32_16x16x32_bf16 v[70:73], v[176:179], v[218:221], v[70:73]
	s_barrier
	s_add_u32 s52, s24, 0x80000
	s_addc_u32 s53, s25, 0
	s_add_i32 s50, s50, s35
	s_mov_b32 m0, s50
	ds_read_b128 v[180:183], v155 offset:16384
	ds_read_b128 v[184:187], v155 offset:17408
	global_load_lds_dwordx4 v0, s[24:25]
	s_add_i32 m0, s50, 0x2000
	s_add_i32 s2, s2, s35
	ds_read_b128 v[188:191], v155 offset:18432
	ds_read_b128 v[192:195], v155 offset:19456
	global_load_lds_dwordx4 v130, s[24:25]
	s_mov_b32 m0, s2
	ds_read_b128 v[206:209], v155 offset:20480
	ds_read_b128 v[210:213], v155 offset:21504
	global_load_lds_dwordx4 v0, s[52:53]
	s_add_i32 m0, s2, 0x2000
	ds_read_b128 v[214:217], v155 offset:22528
	ds_read_b128 v[218:221], v155 offset:23552
	global_load_lds_dwordx4 v130, s[52:53]
	s_waitcnt vmcnt(6)
	s_waitcnt lgkmcnt(0)
	s_barrier
	s_waitcnt lgkmcnt(0)
	v_mfma_f32_16x16x32_bf16 v[58:61], v[140:143], v[180:183], v[58:61]
	v_mfma_f32_16x16x32_bf16 v[50:53], v[156:159], v[180:183], v[50:53]
	v_mfma_f32_16x16x32_bf16 v[42:45], v[140:143], v[188:191], v[42:45]
	v_mfma_f32_16x16x32_bf16 v[34:37], v[156:159], v[188:191], v[34:37]
	v_mfma_f32_16x16x32_bf16 v[26:29], v[140:143], v[206:209], v[26:29]
	v_mfma_f32_16x16x32_bf16 v[18:21], v[156:159], v[206:209], v[18:21]
	v_mfma_f32_16x16x32_bf16 v[10:13], v[140:143], v[214:217], v[10:13]
	v_mfma_f32_16x16x32_bf16 v[6:9], v[156:159], v[214:217], v[6:9]
	v_mfma_f32_16x16x32_bf16 v[58:61], v[148:151], v[184:187], v[58:61]
	v_mfma_f32_16x16x32_bf16 v[50:53], v[160:163], v[184:187], v[50:53]
	v_mfma_f32_16x16x32_bf16 v[42:45], v[148:151], v[192:195], v[42:45]
	v_mfma_f32_16x16x32_bf16 v[34:37], v[160:163], v[192:195], v[34:37]
	v_mfma_f32_16x16x32_bf16 v[26:29], v[148:151], v[210:213], v[26:29]
	v_mfma_f32_16x16x32_bf16 v[18:21], v[160:163], v[210:213], v[18:21]
	v_mfma_f32_16x16x32_bf16 v[10:13], v[148:151], v[218:221], v[10:13]
	v_mfma_f32_16x16x32_bf16 v[6:9], v[160:163], v[218:221], v[6:9]
	v_mfma_f32_16x16x32_bf16 v[62:65], v[164:167], v[180:183], v[62:65]
	v_mfma_f32_16x16x32_bf16 v[54:57], v[172:175], v[180:183], v[54:57]
	v_mfma_f32_16x16x32_bf16 v[46:49], v[164:167], v[188:191], v[46:49]
	v_mfma_f32_16x16x32_bf16 v[38:41], v[172:175], v[188:191], v[38:41]
	v_mfma_f32_16x16x32_bf16 v[30:33], v[164:167], v[206:209], v[30:33]
	v_mfma_f32_16x16x32_bf16 v[22:25], v[172:175], v[206:209], v[22:25]
	v_mfma_f32_16x16x32_bf16 v[14:17], v[164:167], v[214:217], v[14:17]
	v_mfma_f32_16x16x32_bf16 v[2:5], v[172:175], v[214:217], v[2:5]
	v_mfma_f32_16x16x32_bf16 v[62:65], v[168:171], v[184:187], v[62:65]
	v_mfma_f32_16x16x32_bf16 v[54:57], v[176:179], v[184:187], v[54:57]
	v_mfma_f32_16x16x32_bf16 v[46:49], v[168:171], v[192:195], v[46:49]
	v_mfma_f32_16x16x32_bf16 v[38:41], v[176:179], v[192:195], v[38:41]
	v_mfma_f32_16x16x32_bf16 v[30:33], v[168:171], v[210:213], v[30:33]
	v_mfma_f32_16x16x32_bf16 v[22:25], v[176:179], v[210:213], v[22:25]
	v_mfma_f32_16x16x32_bf16 v[14:17], v[168:171], v[218:221], v[14:17]
	v_mfma_f32_16x16x32_bf16 v[2:5], v[176:179], v[218:221], v[2:5]
	s_barrier
	s_add_u32 s28, s28, 0x80000
	s_addc_u32 s29, s29, 0
	s_add_u32 s100, s28, 0xfff80000
	s_addc_u32 s101, s29, -1
	s_add_i32 s2, 0, 0x18000
	s_add_i32 s50, 0, 0x1c000
	v_add_u32_e32 v160, s2, v152
	v_add_u32_e32 v176, s50, v152
	s_mov_b32 m0, s33
	ds_read_b128 v[140:143], v160
	ds_read_b128 v[148:151], v160 offset:1024
	ds_read_b128 v[156:159], v160 offset:2048
	ds_read_b128 v[160:163], v160 offset:3072
	global_load_lds_dwordx4 v134, s[100:101]
	s_mov_b32 m0, s36
	ds_read_b128 v[164:167], v176
	ds_read_b128 v[168:171], v176 offset:1024
	ds_read_b128 v[172:175], v176 offset:2048
	ds_read_b128 v[176:179], v176 offset:3072
	global_load_lds_dwordx4 v132, s[100:101]
	s_mov_b32 m0, s37
	ds_read_b128 v[180:183], v155 offset:32768
	ds_read_b128 v[184:187], v155 offset:33792
	ds_read_b128 v[188:191], v155 offset:34816
	ds_read_b128 v[192:195], v155 offset:35840
	global_load_lds_dwordx4 v134, s[28:29]
	s_mov_b32 m0, s38
	ds_read_b128 v[206:209], v155 offset:36864
	ds_read_b128 v[210:213], v155 offset:37888
	ds_read_b128 v[214:217], v155 offset:38912
	ds_read_b128 v[218:221], v155 offset:39936
	global_load_lds_dwordx4 v132, s[28:29]
	s_waitcnt vmcnt(8)
	s_waitcnt lgkmcnt(0)
	s_barrier
	s_waitcnt lgkmcnt(0)
	v_mfma_f32_16x16x32_bf16 v[122:125], v[140:143], v[180:183], v[122:125]
	v_mfma_f32_16x16x32_bf16 v[114:117], v[156:159], v[180:183], v[114:117]
	v_mfma_f32_16x16x32_bf16 v[106:109], v[140:143], v[188:191], v[106:109]
	v_mfma_f32_16x16x32_bf16 v[98:101], v[156:159], v[188:191], v[98:101]
	v_mfma_f32_16x16x32_bf16 v[90:93], v[140:143], v[206:209], v[90:93]
	v_mfma_f32_16x16x32_bf16 v[82:85], v[156:159], v[206:209], v[82:85]
	v_mfma_f32_16x16x32_bf16 v[74:77], v[140:143], v[214:217], v[74:77]
	v_mfma_f32_16x16x32_bf16 v[66:69], v[156:159], v[214:217], v[66:69]
	v_mfma_f32_16x16x32_bf16 v[122:125], v[148:151], v[184:187], v[122:125]
	v_mfma_f32_16x16x32_bf16 v[114:117], v[160:163], v[184:187], v[114:117]
	v_mfma_f32_16x16x32_bf16 v[106:109], v[148:151], v[192:195], v[106:109]
	v_mfma_f32_16x16x32_bf16 v[98:101], v[160:163], v[192:195], v[98:101]
	v_mfma_f32_16x16x32_bf16 v[90:93], v[148:151], v[210:213], v[90:93]
	v_mfma_f32_16x16x32_bf16 v[82:85], v[160:163], v[210:213], v[82:85]
	v_mfma_f32_16x16x32_bf16 v[74:77], v[148:151], v[218:221], v[74:77]
	v_mfma_f32_16x16x32_bf16 v[66:69], v[160:163], v[218:221], v[66:69]
	v_mfma_f32_16x16x32_bf16 v[126:129], v[164:167], v[180:183], v[126:129]
	v_mfma_f32_16x16x32_bf16 v[118:121], v[172:175], v[180:183], v[118:121]
	v_mfma_f32_16x16x32_bf16 v[110:113], v[164:167], v[188:191], v[110:113]
	v_mfma_f32_16x16x32_bf16 v[102:105], v[172:175], v[188:191], v[102:105]
	v_mfma_f32_16x16x32_bf16 v[94:97], v[164:167], v[206:209], v[94:97]
	v_mfma_f32_16x16x32_bf16 v[86:89], v[172:175], v[206:209], v[86:89]
	v_mfma_f32_16x16x32_bf16 v[78:81], v[164:167], v[214:217], v[78:81]
	v_mfma_f32_16x16x32_bf16 v[70:73], v[172:175], v[214:217], v[70:73]
	v_mfma_f32_16x16x32_bf16 v[126:129], v[168:171], v[184:187], v[126:129]
	v_mfma_f32_16x16x32_bf16 v[118:121], v[176:179], v[184:187], v[118:121]
	v_mfma_f32_16x16x32_bf16 v[110:113], v[168:171], v[192:195], v[110:113]
	v_mfma_f32_16x16x32_bf16 v[102:105], v[176:179], v[192:195], v[102:105]
	v_mfma_f32_16x16x32_bf16 v[94:97], v[168:171], v[210:213], v[94:97]
	v_mfma_f32_16x16x32_bf16 v[86:89], v[176:179], v[210:213], v[86:89]
	v_mfma_f32_16x16x32_bf16 v[78:81], v[168:171], v[218:221], v[78:81]
	v_mfma_f32_16x16x32_bf16 v[70:73], v[176:179], v[218:221], v[70:73]
	s_barrier
	s_add_u32 s24, s24, 0x80080
	s_addc_u32 s25, s25, 0
	s_add_u32 s52, s52, 0xfff80080
	s_addc_u32 s53, s53, -1
	s_add_i32 s2, s2, s35
	s_mov_b32 m0, s2
	ds_read_b128 v[180:183], v155 offset:49152
	ds_read_b128 v[184:187], v155 offset:50176
	global_load_lds_dwordx4 v0, s[52:53]
	s_add_i32 m0, s2, 0x2000
	s_add_i32 s2, s50, s35
	ds_read_b128 v[188:191], v155 offset:51200
	ds_read_b128 v[192:195], v155 offset:52224
	global_load_lds_dwordx4 v130, s[52:53]
	s_mov_b32 m0, s2
	ds_read_b128 v[206:209], v155 offset:53248
	ds_read_b128 v[210:213], v155 offset:54272
	global_load_lds_dwordx4 v0, s[24:25]
	s_add_i32 m0, s2, 0x2000
	ds_read_b128 v[214:217], v155 offset:55296
	ds_read_b128 v[218:221], v155 offset:56320
	global_load_lds_dwordx4 v130, s[24:25]
	s_waitcnt vmcnt(6)
	s_waitcnt lgkmcnt(0)
	s_barrier
	s_waitcnt lgkmcnt(0)
	v_mfma_f32_16x16x32_bf16 v[58:61], v[140:143], v[180:183], v[58:61]
	v_mfma_f32_16x16x32_bf16 v[50:53], v[156:159], v[180:183], v[50:53]
	v_mfma_f32_16x16x32_bf16 v[42:45], v[140:143], v[188:191], v[42:45]
	v_mfma_f32_16x16x32_bf16 v[34:37], v[156:159], v[188:191], v[34:37]
	v_mfma_f32_16x16x32_bf16 v[26:29], v[140:143], v[206:209], v[26:29]
	v_mfma_f32_16x16x32_bf16 v[18:21], v[156:159], v[206:209], v[18:21]
	v_mfma_f32_16x16x32_bf16 v[10:13], v[140:143], v[214:217], v[10:13]
	v_mfma_f32_16x16x32_bf16 v[6:9], v[156:159], v[214:217], v[6:9]
	v_mfma_f32_16x16x32_bf16 v[58:61], v[148:151], v[184:187], v[58:61]
	v_mfma_f32_16x16x32_bf16 v[50:53], v[160:163], v[184:187], v[50:53]
	v_mfma_f32_16x16x32_bf16 v[42:45], v[148:151], v[192:195], v[42:45]
	v_mfma_f32_16x16x32_bf16 v[34:37], v[160:163], v[192:195], v[34:37]
	v_mfma_f32_16x16x32_bf16 v[26:29], v[148:151], v[210:213], v[26:29]
	v_mfma_f32_16x16x32_bf16 v[18:21], v[160:163], v[210:213], v[18:21]
	v_mfma_f32_16x16x32_bf16 v[10:13], v[148:151], v[218:221], v[10:13]
	v_mfma_f32_16x16x32_bf16 v[6:9], v[160:163], v[218:221], v[6:9]
	v_mfma_f32_16x16x32_bf16 v[62:65], v[164:167], v[180:183], v[62:65]
	v_mfma_f32_16x16x32_bf16 v[54:57], v[172:175], v[180:183], v[54:57]
	v_mfma_f32_16x16x32_bf16 v[46:49], v[164:167], v[188:191], v[46:49]
	v_mfma_f32_16x16x32_bf16 v[38:41], v[172:175], v[188:191], v[38:41]
	v_mfma_f32_16x16x32_bf16 v[30:33], v[164:167], v[206:209], v[30:33]
	v_mfma_f32_16x16x32_bf16 v[22:25], v[172:175], v[206:209], v[22:25]
	v_mfma_f32_16x16x32_bf16 v[14:17], v[164:167], v[214:217], v[14:17]
	v_mfma_f32_16x16x32_bf16 v[2:5], v[172:175], v[214:217], v[2:5]
	v_mfma_f32_16x16x32_bf16 v[62:65], v[168:171], v[184:187], v[62:65]
	v_mfma_f32_16x16x32_bf16 v[54:57], v[176:179], v[184:187], v[54:57]
	v_mfma_f32_16x16x32_bf16 v[46:49], v[168:171], v[192:195], v[46:49]
	v_mfma_f32_16x16x32_bf16 v[38:41], v[176:179], v[192:195], v[38:41]
	v_mfma_f32_16x16x32_bf16 v[30:33], v[168:171], v[210:213], v[30:33]
	v_mfma_f32_16x16x32_bf16 v[22:25], v[176:179], v[210:213], v[22:25]
	v_mfma_f32_16x16x32_bf16 v[14:17], v[168:171], v[218:221], v[14:17]
	v_mfma_f32_16x16x32_bf16 v[2:5], v[176:179], v[218:221], v[2:5]
	s_barrier
	s_add_i32 s49, s49, 2
	s_add_u32 s26, s26, 0x100
	s_addc_u32 s27, s27, 0
	s_add_u32 s46, s46, 0x100
	s_addc_u32 s47, s47, 0
	s_cmp_gt_u32 s49, 29
	s_cbranch_scc0 .LBB0_168
	s_and_b64 vcc, exec, s[14:15]
	s_cbranch_vccz .LBB0_171
	s_barrier

.LBB0_281:
	s_add_u32 s20, s18, 0x100
	s_addc_u32 s21, s19, 0
	s_add_i32 s2, 0, 0x10000
	s_cmpk_eq_i32 s42, 0x52
	s_cselect_b32 s25, s11, s21
	s_cselect_b32 s24, s10, s20
	s_cselect_b32 s23, s17, s41
	s_cselect_b32 s22, s16, s40
	s_add_u32 s100, s18, 0xffea8000
	s_addc_u32 s101, s19, -1
	s_add_i32 s43, 0, 0x14000
	v_add_u32_e32 v142, s2, v226
	v_add_u32_e32 v160, s43, v226
	s_mov_b32 m0, s36
	ds_read_b128 v[126:129], v142
	ds_read_b128 v[134:137], v142 offset:1024
	ds_read_b128 v[138:141], v142 offset:2048
	ds_read_b128 v[142:145], v142 offset:3072
	global_load_lds_dwordx4 v194, s[100:101]
	s_mov_b32 m0, s37
	ds_read_b128 v[148:151], v160
	ds_read_b128 v[152:155], v160 offset:1024
	ds_read_b128 v[156:159], v160 offset:2048
	ds_read_b128 v[160:163], v160 offset:3072
	global_load_lds_dwordx4 v206, s[100:101]
	s_add_i32 m0, s26, 0xc000
	ds_read_b128 v[164:167], v228
	ds_read_b128 v[168:171], v228 offset:1024
	ds_read_b128 v[172:175], v228 offset:2048
	ds_read_b128 v[176:179], v228 offset:3072
	global_load_lds_dwordx4 v194, s[18:19]
	s_add_i32 m0, s26, 0xe000
	ds_read_b128 v[180:183], v228 offset:4096
	ds_read_b128 v[184:187], v228 offset:5120
	ds_read_b128 v[208:211], v228 offset:6144
	ds_read_b128 v[212:215], v228 offset:7168
	global_load_lds_dwordx4 v206, s[18:19]
	s_waitcnt vmcnt(8)
	s_waitcnt lgkmcnt(0)
	s_barrier
	s_waitcnt lgkmcnt(0)
	v_mfma_f32_16x16x32_bf16 v[130:133], v[126:129], v[164:167], v[130:133]
	v_mfma_f32_16x16x32_bf16 v[122:125], v[138:141], v[164:167], v[122:125]
	v_mfma_f32_16x16x32_bf16 v[110:113], v[126:129], v[172:175], v[110:113]
	v_mfma_f32_16x16x32_bf16 v[106:109], v[138:141], v[172:175], v[106:109]
	v_mfma_f32_16x16x32_bf16 v[94:97], v[126:129], v[180:183], v[94:97]
	v_mfma_f32_16x16x32_bf16 v[90:93], v[138:141], v[180:183], v[90:93]
	v_mfma_f32_16x16x32_bf16 v[78:81], v[126:129], v[208:211], v[78:81]
	v_mfma_f32_16x16x32_bf16 v[74:77], v[138:141], v[208:211], v[74:77]
	v_mfma_f32_16x16x32_bf16 v[130:133], v[134:137], v[168:171], v[130:133]
	v_mfma_f32_16x16x32_bf16 v[122:125], v[142:145], v[168:171], v[122:125]
	v_mfma_f32_16x16x32_bf16 v[110:113], v[134:137], v[176:179], v[110:113]
	v_mfma_f32_16x16x32_bf16 v[106:109], v[142:145], v[176:179], v[106:109]
	v_mfma_f32_16x16x32_bf16 v[94:97], v[134:137], v[184:187], v[94:97]
	v_mfma_f32_16x16x32_bf16 v[90:93], v[142:145], v[184:187], v[90:93]
	v_mfma_f32_16x16x32_bf16 v[78:81], v[134:137], v[212:215], v[78:81]
	v_mfma_f32_16x16x32_bf16 v[74:77], v[142:145], v[212:215], v[74:77]
	v_mfma_f32_16x16x32_bf16 v[118:121], v[148:151], v[164:167], v[118:121]
	v_mfma_f32_16x16x32_bf16 v[114:117], v[156:159], v[164:167], v[114:117]
	v_mfma_f32_16x16x32_bf16 v[102:105], v[148:151], v[172:175], v[102:105]
	v_mfma_f32_16x16x32_bf16 v[98:101], v[156:159], v[172:175], v[98:101]
	v_mfma_f32_16x16x32_bf16 v[86:89], v[148:151], v[180:183], v[86:89]
	v_mfma_f32_16x16x32_bf16 v[82:85], v[156:159], v[180:183], v[82:85]
	v_mfma_f32_16x16x32_bf16 v[70:73], v[148:151], v[208:211], v[70:73]
	v_mfma_f32_16x16x32_bf16 v[66:69], v[156:159], v[208:211], v[66:69]
	v_mfma_f32_16x16x32_bf16 v[118:121], v[152:155], v[168:171], v[118:121]
	v_mfma_f32_16x16x32_bf16 v[114:117], v[160:163], v[168:171], v[114:117]
	v_mfma_f32_16x16x32_bf16 v[102:105], v[152:155], v[176:179], v[102:105]
	v_mfma_f32_16x16x32_bf16 v[98:101], v[160:163], v[176:179], v[98:101]
	v_mfma_f32_16x16x32_bf16 v[86:89], v[152:155], v[184:187], v[86:89]
	v_mfma_f32_16x16x32_bf16 v[82:85], v[160:163], v[184:187], v[82:85]
	v_mfma_f32_16x16x32_bf16 v[70:73], v[152:155], v[212:215], v[70:73]
	v_mfma_f32_16x16x32_bf16 v[66:69], v[160:163], v[212:215], v[66:69]
	s_barrier
	s_add_u32 s18, s22, 0x158000
	s_addc_u32 s19, s23, 0
	s_add_i32 s2, s2, s1
	s_mov_b32 m0, s2
	ds_read_b128 v[164:167], v228 offset:16384
	ds_read_b128 v[168:171], v228 offset:17408
	global_load_lds_dwordx4 v0, s[22:23]
	s_add_i32 m0, s2, 0x2000
	s_add_i32 s2, s43, s1
	ds_read_b128 v[172:175], v228 offset:18432
	ds_read_b128 v[176:179], v228 offset:19456
	global_load_lds_dwordx4 v188, s[22:23]
	s_mov_b32 m0, s2
	ds_read_b128 v[180:183], v228 offset:20480
	ds_read_b128 v[184:187], v228 offset:21504
	global_load_lds_dwordx4 v0, s[18:19]
	s_add_i32 m0, s2, 0x2000
	ds_read_b128 v[208:211], v228 offset:22528
	ds_read_b128 v[212:215], v228 offset:23552
	global_load_lds_dwordx4 v188, s[18:19]
	s_waitcnt vmcnt(6)
	s_waitcnt lgkmcnt(0)
	s_barrier
	s_waitcnt lgkmcnt(0)
	v_mfma_f32_16x16x32_bf16 v[62:65], v[126:129], v[164:167], v[62:65]
	v_mfma_f32_16x16x32_bf16 v[58:61], v[138:141], v[164:167], v[58:61]
	v_mfma_f32_16x16x32_bf16 v[46:49], v[126:129], v[172:175], v[46:49]
	v_mfma_f32_16x16x32_bf16 v[42:45], v[138:141], v[172:175], v[42:45]
	v_mfma_f32_16x16x32_bf16 v[30:33], v[126:129], v[180:183], v[30:33]
	v_mfma_f32_16x16x32_bf16 v[26:29], v[138:141], v[180:183], v[26:29]
	v_mfma_f32_16x16x32_bf16 v[14:17], v[126:129], v[208:211], v[14:17]
	v_mfma_f32_16x16x32_bf16 v[10:13], v[138:141], v[208:211], v[10:13]
	v_mfma_f32_16x16x32_bf16 v[62:65], v[134:137], v[168:171], v[62:65]
	v_mfma_f32_16x16x32_bf16 v[58:61], v[142:145], v[168:171], v[58:61]
	v_mfma_f32_16x16x32_bf16 v[46:49], v[134:137], v[176:179], v[46:49]
	v_mfma_f32_16x16x32_bf16 v[42:45], v[142:145], v[176:179], v[42:45]
	v_mfma_f32_16x16x32_bf16 v[30:33], v[134:137], v[184:187], v[30:33]
	v_mfma_f32_16x16x32_bf16 v[26:29], v[142:145], v[184:187], v[26:29]
	v_mfma_f32_16x16x32_bf16 v[14:17], v[134:137], v[212:215], v[14:17]
	v_mfma_f32_16x16x32_bf16 v[10:13], v[142:145], v[212:215], v[10:13]
	v_mfma_f32_16x16x32_bf16 v[54:57], v[148:151], v[164:167], v[54:57]
	v_mfma_f32_16x16x32_bf16 v[50:53], v[156:159], v[164:167], v[50:53]
	v_mfma_f32_16x16x32_bf16 v[38:41], v[148:151], v[172:175], v[38:41]
	v_mfma_f32_16x16x32_bf16 v[34:37], v[156:159], v[172:175], v[34:37]
	v_mfma_f32_16x16x32_bf16 v[22:25], v[148:151], v[180:183], v[22:25]
	v_mfma_f32_16x16x32_bf16 v[18:21], v[156:159], v[180:183], v[18:21]
	v_mfma_f32_16x16x32_bf16 v[6:9], v[148:151], v[208:211], v[6:9]
	v_mfma_f32_16x16x32_bf16 v[2:5], v[156:159], v[208:211], v[2:5]
	v_mfma_f32_16x16x32_bf16 v[54:57], v[152:155], v[168:171], v[54:57]
	v_mfma_f32_16x16x32_bf16 v[50:53], v[160:163], v[168:171], v[50:53]
	v_mfma_f32_16x16x32_bf16 v[38:41], v[152:155], v[176:179], v[38:41]
	v_mfma_f32_16x16x32_bf16 v[34:37], v[160:163], v[176:179], v[34:37]
	v_mfma_f32_16x16x32_bf16 v[22:25], v[152:155], v[184:187], v[22:25]
	v_mfma_f32_16x16x32_bf16 v[18:21], v[160:163], v[184:187], v[18:21]
	v_mfma_f32_16x16x32_bf16 v[6:9], v[152:155], v[212:215], v[6:9]
	v_mfma_f32_16x16x32_bf16 v[2:5], v[160:163], v[212:215], v[2:5]
	s_barrier
	s_add_u32 s18, s24, 0x158000
	s_addc_u32 s19, s25, 0
	s_add_i32 s2, 0, 0x18000
	s_add_i32 s43, 0, 0x1c000
	v_add_u32_e32 v142, s2, v226
	v_add_u32_e32 v160, s43, v226
	s_mov_b32 m0, s26
	ds_read_b128 v[126:129], v142
	ds_read_b128 v[134:137], v142 offset:1024
	ds_read_b128 v[138:141], v142 offset:2048
	ds_read_b128 v[142:145], v142 offset:3072
	global_load_lds_dwordx4 v192, s[24:25]
	s_mov_b32 m0, s27
	ds_read_b128 v[148:151], v160
	ds_read_b128 v[152:155], v160 offset:1024
	ds_read_b128 v[156:159], v160 offset:2048
	ds_read_b128 v[160:163], v160 offset:3072
	global_load_lds_dwordx4 v190, s[24:25]
	s_mov_b32 m0, s30
	ds_read_b128 v[164:167], v228 offset:32768
	ds_read_b128 v[168:171], v228 offset:33792
	ds_read_b128 v[172:175], v228 offset:34816
	ds_read_b128 v[176:179], v228 offset:35840
	global_load_lds_dwordx4 v192, s[18:19]
	s_mov_b32 m0, s31
	ds_read_b128 v[180:183], v228 offset:36864
	ds_read_b128 v[184:187], v228 offset:37888
	ds_read_b128 v[208:211], v228 offset:38912
	ds_read_b128 v[212:215], v228 offset:39936
	global_load_lds_dwordx4 v190, s[18:19]
	s_waitcnt vmcnt(8)
	s_waitcnt lgkmcnt(0)
	s_barrier
	s_waitcnt lgkmcnt(0)
	v_mfma_f32_16x16x32_bf16 v[130:133], v[126:129], v[164:167], v[130:133]
	v_mfma_f32_16x16x32_bf16 v[122:125], v[138:141], v[164:167], v[122:125]
	v_mfma_f32_16x16x32_bf16 v[110:113], v[126:129], v[172:175], v[110:113]
	v_mfma_f32_16x16x32_bf16 v[106:109], v[138:141], v[172:175], v[106:109]
	v_mfma_f32_16x16x32_bf16 v[94:97], v[126:129], v[180:183], v[94:97]
	v_mfma_f32_16x16x32_bf16 v[90:93], v[138:141], v[180:183], v[90:93]
	v_mfma_f32_16x16x32_bf16 v[78:81], v[126:129], v[208:211], v[78:81]
	v_mfma_f32_16x16x32_bf16 v[74:77], v[138:141], v[208:211], v[74:77]
	v_mfma_f32_16x16x32_bf16 v[130:133], v[134:137], v[168:171], v[130:133]
	v_mfma_f32_16x16x32_bf16 v[122:125], v[142:145], v[168:171], v[122:125]
	v_mfma_f32_16x16x32_bf16 v[110:113], v[134:137], v[176:179], v[110:113]
	v_mfma_f32_16x16x32_bf16 v[106:109], v[142:145], v[176:179], v[106:109]
	v_mfma_f32_16x16x32_bf16 v[94:97], v[134:137], v[184:187], v[94:97]
	v_mfma_f32_16x16x32_bf16 v[90:93], v[142:145], v[184:187], v[90:93]
	v_mfma_f32_16x16x32_bf16 v[78:81], v[134:137], v[212:215], v[78:81]
	v_mfma_f32_16x16x32_bf16 v[74:77], v[142:145], v[212:215], v[74:77]
	v_mfma_f32_16x16x32_bf16 v[118:121], v[148:151], v[164:167], v[118:121]
	v_mfma_f32_16x16x32_bf16 v[114:117], v[156:159], v[164:167], v[114:117]
	v_mfma_f32_16x16x32_bf16 v[102:105], v[148:151], v[172:175], v[102:105]
	v_mfma_f32_16x16x32_bf16 v[98:101], v[156:159], v[172:175], v[98:101]
	v_mfma_f32_16x16x32_bf16 v[86:89], v[148:151], v[180:183], v[86:89]
	v_mfma_f32_16x16x32_bf16 v[82:85], v[156:159], v[180:183], v[82:85]
	v_mfma_f32_16x16x32_bf16 v[70:73], v[148:151], v[208:211], v[70:73]
	v_mfma_f32_16x16x32_bf16 v[66:69], v[156:159], v[208:211], v[66:69]
	v_mfma_f32_16x16x32_bf16 v[118:121], v[152:155], v[168:171], v[118:121]
	v_mfma_f32_16x16x32_bf16 v[114:117], v[160:163], v[168:171], v[114:117]
	v_mfma_f32_16x16x32_bf16 v[102:105], v[152:155], v[176:179], v[102:105]
	v_mfma_f32_16x16x32_bf16 v[98:101], v[160:163], v[176:179], v[98:101]
	v_mfma_f32_16x16x32_bf16 v[86:89], v[152:155], v[184:187], v[86:89]
	v_mfma_f32_16x16x32_bf16 v[82:85], v[160:163], v[184:187], v[82:85]
	v_mfma_f32_16x16x32_bf16 v[70:73], v[152:155], v[212:215], v[70:73]
	v_mfma_f32_16x16x32_bf16 v[66:69], v[160:163], v[212:215], v[66:69]
	s_barrier
	s_add_u32 s18, s22, 0x158080
	s_addc_u32 s19, s23, 0
	s_add_u32 s22, s22, 0x80
	s_addc_u32 s23, s23, 0
	s_add_i32 s2, s2, s1
	s_mov_b32 m0, s2
	ds_read_b128 v[164:167], v228 offset:49152
	ds_read_b128 v[168:171], v228 offset:50176
	global_load_lds_dwordx4 v0, s[22:23]
	s_add_i32 m0, s2, 0x2000
	s_add_i32 s2, s43, s1
	ds_read_b128 v[172:175], v228 offset:51200
	ds_read_b128 v[176:179], v228 offset:52224
	global_load_lds_dwordx4 v188, s[22:23]
	s_mov_b32 m0, s2
	ds_read_b128 v[180:183], v228 offset:53248
	ds_read_b128 v[184:187], v228 offset:54272
	global_load_lds_dwordx4 v0, s[18:19]
	s_add_i32 m0, s2, 0x2000
	ds_read_b128 v[208:211], v228 offset:55296
	ds_read_b128 v[212:215], v228 offset:56320
	global_load_lds_dwordx4 v188, s[18:19]
	s_waitcnt vmcnt(6)
	s_waitcnt lgkmcnt(0)
	s_barrier
	s_waitcnt lgkmcnt(0)
	v_mfma_f32_16x16x32_bf16 v[62:65], v[126:129], v[164:167], v[62:65]
	v_mfma_f32_16x16x32_bf16 v[58:61], v[138:141], v[164:167], v[58:61]
	v_mfma_f32_16x16x32_bf16 v[46:49], v[126:129], v[172:175], v[46:49]
	v_mfma_f32_16x16x32_bf16 v[42:45], v[138:141], v[172:175], v[42:45]
	v_mfma_f32_16x16x32_bf16 v[30:33], v[126:129], v[180:183], v[30:33]
	v_mfma_f32_16x16x32_bf16 v[26:29], v[138:141], v[180:183], v[26:29]
	v_mfma_f32_16x16x32_bf16 v[14:17], v[126:129], v[208:211], v[14:17]
	v_mfma_f32_16x16x32_bf16 v[10:13], v[138:141], v[208:211], v[10:13]
	v_mfma_f32_16x16x32_bf16 v[62:65], v[134:137], v[168:171], v[62:65]
	v_mfma_f32_16x16x32_bf16 v[58:61], v[142:145], v[168:171], v[58:61]
	v_mfma_f32_16x16x32_bf16 v[46:49], v[134:137], v[176:179], v[46:49]
	v_mfma_f32_16x16x32_bf16 v[42:45], v[142:145], v[176:179], v[42:45]
	v_mfma_f32_16x16x32_bf16 v[30:33], v[134:137], v[184:187], v[30:33]
	v_mfma_f32_16x16x32_bf16 v[26:29], v[142:145], v[184:187], v[26:29]
	v_mfma_f32_16x16x32_bf16 v[14:17], v[134:137], v[212:215], v[14:17]
	v_mfma_f32_16x16x32_bf16 v[10:13], v[142:145], v[212:215], v[10:13]
	v_mfma_f32_16x16x32_bf16 v[54:57], v[148:151], v[164:167], v[54:57]
	v_mfma_f32_16x16x32_bf16 v[50:53], v[156:159], v[164:167], v[50:53]
	v_mfma_f32_16x16x32_bf16 v[38:41], v[148:151], v[172:175], v[38:41]
	v_mfma_f32_16x16x32_bf16 v[34:37], v[156:159], v[172:175], v[34:37]
	v_mfma_f32_16x16x32_bf16 v[22:25], v[148:151], v[180:183], v[22:25]
	v_mfma_f32_16x16x32_bf16 v[18:21], v[156:159], v[180:183], v[18:21]
	v_mfma_f32_16x16x32_bf16 v[6:9], v[148:151], v[208:211], v[6:9]
	v_mfma_f32_16x16x32_bf16 v[2:5], v[156:159], v[208:211], v[2:5]
	v_mfma_f32_16x16x32_bf16 v[54:57], v[152:155], v[168:171], v[54:57]
	v_mfma_f32_16x16x32_bf16 v[50:53], v[160:163], v[168:171], v[50:53]
	v_mfma_f32_16x16x32_bf16 v[38:41], v[152:155], v[176:179], v[38:41]
	v_mfma_f32_16x16x32_bf16 v[34:37], v[160:163], v[176:179], v[34:37]
	v_mfma_f32_16x16x32_bf16 v[22:25], v[152:155], v[184:187], v[22:25]
	v_mfma_f32_16x16x32_bf16 v[18:21], v[160:163], v[184:187], v[18:21]
	v_mfma_f32_16x16x32_bf16 v[6:9], v[152:155], v[212:215], v[6:9]
	v_mfma_f32_16x16x32_bf16 v[2:5], v[160:163], v[212:215], v[2:5]
	s_barrier
	s_add_i32 s42, s42, 2
	s_add_u32 s40, s40, 0x100
	s_addc_u32 s41, s41, 0
	s_cmpk_gt_u32 s42, 0x53
	s_mov_b64 s[18:19], s[20:21]
	s_cbranch_scc0 .LBB0_281
	s_nop 0
	s_nop 0
	s_nop 0
	v_lshl_or_b32 v210, s3, 8, v227
	v_lshl_add_u32 v224, s34, 8, v147
	v_ashrrev_i32_e32 v211, 31, v210
	v_lshlrev_b64 v[126:127], 1, v[210:211]
	v_ashrrev_i32_e32 v225, 31, v224
	v_lshl_add_u64 v[128:129], s[12:13], 0, v[126:127]
	v_lshlrev_b64 v[134:135], 12, v[224:225]
	v_lshl_add_u64 v[136:137], v[128:129], 0, v[134:135]
	global_load_dwordx4 v[240:243], v[136:137], off
	global_load_dwordx4 v[244:247], v[136:137], off offset:256
	v_or_b32_e32 v222, 16, v224
	v_or_b32_e32 v220, 32, v224
	v_or_b32_e32 v218, 48, v224
	v_add_u32_e32 v216, 0x80, v224
	v_add_u32_e32 v214, 0x90, v224
	v_add_u32_e32 v212, 0xa0, v224
	v_add_u32_e32 v208, 0xb0, v224
	v_ashrrev_i32_e32 v223, 31, v222
	v_ashrrev_i32_e32 v221, 31, v220
	v_ashrrev_i32_e32 v219, 31, v218
	v_ashrrev_i32_e32 v217, 31, v216
	v_ashrrev_i32_e32 v215, 31, v214
	v_ashrrev_i32_e32 v213, 31, v212
	v_ashrrev_i32_e32 v209, 31, v208
	v_lshlrev_b64 v[136:137], 12, v[222:223]
	v_lshlrev_b64 v[138:139], 12, v[220:221]
	v_lshlrev_b64 v[140:141], 12, v[218:219]
	v_lshlrev_b64 v[142:143], 12, v[216:217]
	v_lshlrev_b64 v[144:145], 12, v[214:215]
	v_lshlrev_b64 v[148:149], 12, v[212:213]
	v_lshlrev_b64 v[150:151], 12, v[208:209]
	v_lshl_add_u64 v[134:135], s[12:13], 0, v[134:135]
	v_lshl_add_u64 v[136:137], v[128:129], 0, v[136:137]
	v_lshl_add_u64 v[138:139], v[128:129], 0, v[138:139]
	v_lshl_add_u64 v[140:141], v[128:129], 0, v[140:141]
	v_lshl_add_u64 v[142:143], v[128:129], 0, v[142:143]
	v_lshl_add_u64 v[144:145], v[128:129], 0, v[144:145]
	v_lshl_add_u64 v[248:249], v[128:129], 0, v[148:149]
	v_lshl_add_u64 v[128:129], v[128:129], 0, v[150:151]
	v_lshl_add_u64 v[250:251], v[134:135], 0, v[126:127]
	global_load_dwordx4 v[184:187], v[136:137], off
	global_load_dwordx4 v[180:183], v[136:137], off offset:256
	global_load_dwordx4 v[176:179], v[138:139], off
	global_load_dwordx4 v[172:175], v[138:139], off offset:256
	global_load_dwordx4 v[168:171], v[140:141], off
	global_load_dwordx4 v[164:167], v[140:141], off offset:256
	global_load_dwordx4 v[160:163], v[142:143], off
	global_load_dwordx4 v[156:159], v[142:143], off offset:256
	global_load_dwordx4 v[152:155], v[144:145], off
	global_load_dwordx4 v[148:151], v[144:145], off offset:256
	s_nop 0
	global_load_dwordx4 v[142:145], v[248:249], off
	global_load_dwordx4 v[138:141], v[248:249], off offset:256
	global_load_dwordx4 v[134:137], v[128:129], off
	s_nop 0
	global_load_dwordx4 v[126:129], v[128:129], off offset:256
	s_lshl_b32 s18, s3, 2
	s_ashr_i32 s19, s18, 31
	s_waitcnt vmcnt(0)
	v_lshlrev_b32_e32 v248, 16, v240
	v_and_b32_e32 v249, 0xffff0000, v240
	v_lshlrev_b32_e32 v240, 16, v241
	v_and_b32_e32 v241, 0xffff0000, v241
	v_lshlrev_b32_e32 v252, 16, v242
	v_and_b32_e32 v253, 0xffff0000, v242
	v_lshlrev_b32_e32 v242, 16, v243
	v_and_b32_e32 v243, 0xffff0000, v243
	v_pk_fma_f32 v[132:133], v[132:133], 0.5, v[240:241] op_sel_hi:[1,0,1]
	v_pk_fma_f32 v[240:241], v[124:125], 0.5, v[242:243] op_sel_hi:[1,0,1]
	v_pk_fma_f32 v[124:125], v[122:123], 0.5, v[252:253] op_sel_hi:[1,0,1]
	v_pk_fma_f32 v[130:131], v[130:131], 0.5, v[248:249] op_sel_hi:[1,0,1]
	v_lshlrev_b32_e32 v236, 16, v244
	v_cvt_pk_bf16_f32 v122, v130, v131
	v_cvt_pk_bf16_f32 v123, v132, v133
	v_cvt_pk_bf16_f32 v124, v124, v125
	v_cvt_pk_bf16_f32 v125, v240, v241
	global_store_dwordx4 v[250:251], v[122:125], off
	v_lshlrev_b32_e32 v130, 16, v122
	v_lshlrev_b32_e32 v131, 16, v123
	v_and_b32_e32 v122, 0xffff0000, v122
	v_and_b32_e32 v123, 0xffff0000, v123
	v_lshlrev_b32_e32 v132, 16, v124
	v_and_b32_e32 v124, 0xffff0000, v124
	v_lshlrev_b32_e32 v133, 16, v125
	v_and_b32_e32 v125, 0xffff0000, v125
	v_mul_f32_e32 v122, v122, v122
	v_mul_f32_e32 v123, v123, v123
	v_mul_f32_e32 v124, v124, v124
	v_mul_f32_e32 v125, v125, v125
	v_fmac_f32_e32 v122, v130, v130
	v_fmac_f32_e32 v123, v131, v131
	v_fmac_f32_e32 v124, v132, v132
	v_fmac_f32_e32 v125, v133, v133
	v_add_f32_e32 v122, v122, v123
	v_add_f32_e32 v123, v124, v125
	v_and_b32_e32 v237, 0xffff0000, v244
	v_add_f32_e32 v132, v122, v123
	v_lshlrev_b32_e32 v122, 16, v245
	v_and_b32_e32 v123, 0xffff0000, v245
	v_lshlrev_b32_e32 v124, 16, v246
	v_and_b32_e32 v125, 0xffff0000, v246
	v_lshlrev_b32_e32 v130, 16, v247
	v_and_b32_e32 v131, 0xffff0000, v247
	v_pk_fma_f32 v[120:121], v[120:121], 0.5, v[122:123] op_sel_hi:[1,0,1]
	v_pk_fma_f32 v[118:119], v[118:119], 0.5, v[236:237] op_sel_hi:[1,0,1]
	v_pk_fma_f32 v[122:123], v[116:117], 0.5, v[130:131] op_sel_hi:[1,0,1]
	v_pk_fma_f32 v[116:117], v[114:115], 0.5, v[124:125] op_sel_hi:[1,0,1]
	v_cvt_pk_bf16_f32 v114, v118, v119
	v_cvt_pk_bf16_f32 v115, v120, v121
	s_nop 0
	v_cvt_pk_bf16_f32 v116, v116, v117
	v_cvt_pk_bf16_f32 v117, v122, v123
	global_store_dwordx4 v[250:251], v[114:117], off offset:256
	v_lshlrev_b32_e32 v118, 16, v114
	v_lshlrev_b32_e32 v119, 16, v115
	v_and_b32_e32 v114, 0xffff0000, v114
	v_and_b32_e32 v115, 0xffff0000, v115
	v_mul_f32_e32 v114, v114, v114
	v_mul_f32_e32 v115, v115, v115
	v_lshlrev_b32_e32 v120, 16, v116
	v_and_b32_e32 v116, 0xffff0000, v116
	v_lshlrev_b32_e32 v121, 16, v117
	v_and_b32_e32 v117, 0xffff0000, v117
	v_fmac_f32_e32 v114, v118, v118
	v_fmac_f32_e32 v115, v119, v119
	v_add_f32_e32 v114, v114, v115
	v_mul_f32_e32 v115, v116, v116
	v_mul_f32_e32 v116, v117, v117
	v_fmac_f32_e32 v115, v120, v120
	v_fmac_f32_e32 v116, v121, v121
	v_add_f32_e32 v115, v115, v116
	v_add_f32_e32 v114, v114, v115
	s_mov_b32 s2, 0
	v_add_f32_e32 v114, v132, v114
	v_mbcnt_lo_u32_b32 v115, -1, s2
	v_mbcnt_hi_u32_b32 v115, -1, v115
	v_lshlrev_b32_e32 v115, 2, v115
	v_xor_b32_e32 v115, 64, v115
	ds_bpermute_b32 v115, v115, v114
	s_mov_b32 s2, 0
	s_waitcnt lgkmcnt(0)
	v_add_f32_e32 v114, v114, v115
	v_mbcnt_lo_u32_b32 v115, -1, s2
	v_mbcnt_hi_u32_b32 v115, -1, v115
	v_lshlrev_b32_e32 v115, 2, v115
	v_xor_b32_e32 v115, 0x80, v115
	ds_bpermute_b32 v115, v115, v114
	s_and_saveexec_b64 s[20:21], s[6:7]
	s_cbranch_execz .LBB0_284
	v_lshlrev_b64 v[116:117], 7, v[224:225]
	v_lshl_add_u64 v[116:117], s[14:15], 0, v[116:117]
	v_lshl_add_u64 v[116:117], s[18:19], 2, v[116:117]
	s_lshl_b32 s50, s35, 2
	v_lshl_add_u64 v[116:117], v[116:117], 0, s[50:51]
	s_waitcnt lgkmcnt(0)
	v_add_f32_e32 v114, v114, v115
	global_store_dword v[116:117], v114, off

.LBB0_322:
	s_add_u32 s22, s20, 0x100
	s_addc_u32 s23, s21, 0
	s_add_i32 s2, 0, 0x10000
	s_cmpk_eq_i32 s42, 0x52
	s_cselect_b32 s27, s9, s23
	s_cselect_b32 s26, s8, s22
	s_cselect_b32 s25, s19, s41
	s_cselect_b32 s24, s18, s40
	s_add_u32 s100, s20, 0xffea8000
	s_addc_u32 s101, s21, -1
	s_add_i32 s43, 0, 0x14000
	v_add_u32_e32 v142, s2, v240
	v_add_u32_e32 v160, s43, v240
	s_mov_b32 m0, s35
	ds_read_b128 v[130:133], v142
	ds_read_b128 v[134:137], v142 offset:1024
	ds_read_b128 v[138:141], v142 offset:2048
	ds_read_b128 v[142:145], v142 offset:3072
	global_load_lds_dwordx4 v208, s[100:101]
	s_mov_b32 m0, s36
	ds_read_b128 v[148:151], v160
	ds_read_b128 v[152:155], v160 offset:1024
	ds_read_b128 v[156:159], v160 offset:2048
	ds_read_b128 v[160:163], v160 offset:3072
	global_load_lds_dwordx4 v210, s[100:101]
	s_add_i32 m0, s1, 0xc000
	ds_read_b128 v[164:167], v242
	ds_read_b128 v[168:171], v242 offset:1024
	ds_read_b128 v[172:175], v242 offset:2048
	ds_read_b128 v[176:179], v242 offset:3072
	global_load_lds_dwordx4 v208, s[20:21]
	s_add_i32 m0, s1, 0xe000
	ds_read_b128 v[180:183], v242 offset:4096
	ds_read_b128 v[184:187], v242 offset:5120
	ds_read_b128 v[188:191], v242 offset:6144
	ds_read_b128 v[212:215], v242 offset:7168
	global_load_lds_dwordx4 v210, s[20:21]
	s_waitcnt vmcnt(8)
	s_waitcnt lgkmcnt(0)
	s_barrier
	s_waitcnt lgkmcnt(0)
	v_mfma_f32_16x16x32_bf16 v[126:129], v[130:133], v[164:167], v[126:129]
	v_mfma_f32_16x16x32_bf16 v[122:125], v[138:141], v[164:167], v[122:125]
	v_mfma_f32_16x16x32_bf16 v[110:113], v[130:133], v[172:175], v[110:113]
	v_mfma_f32_16x16x32_bf16 v[106:109], v[138:141], v[172:175], v[106:109]
	v_mfma_f32_16x16x32_bf16 v[94:97], v[130:133], v[180:183], v[94:97]
	v_mfma_f32_16x16x32_bf16 v[90:93], v[138:141], v[180:183], v[90:93]
	v_mfma_f32_16x16x32_bf16 v[78:81], v[130:133], v[188:191], v[78:81]
	v_mfma_f32_16x16x32_bf16 v[74:77], v[138:141], v[188:191], v[74:77]
	v_mfma_f32_16x16x32_bf16 v[126:129], v[134:137], v[168:171], v[126:129]
	v_mfma_f32_16x16x32_bf16 v[122:125], v[142:145], v[168:171], v[122:125]
	v_mfma_f32_16x16x32_bf16 v[110:113], v[134:137], v[176:179], v[110:113]
	v_mfma_f32_16x16x32_bf16 v[106:109], v[142:145], v[176:179], v[106:109]
	v_mfma_f32_16x16x32_bf16 v[94:97], v[134:137], v[184:187], v[94:97]
	v_mfma_f32_16x16x32_bf16 v[90:93], v[142:145], v[184:187], v[90:93]
	v_mfma_f32_16x16x32_bf16 v[78:81], v[134:137], v[212:215], v[78:81]
	v_mfma_f32_16x16x32_bf16 v[74:77], v[142:145], v[212:215], v[74:77]
	v_mfma_f32_16x16x32_bf16 v[118:121], v[148:151], v[164:167], v[118:121]
	v_mfma_f32_16x16x32_bf16 v[114:117], v[156:159], v[164:167], v[114:117]
	v_mfma_f32_16x16x32_bf16 v[102:105], v[148:151], v[172:175], v[102:105]
	v_mfma_f32_16x16x32_bf16 v[98:101], v[156:159], v[172:175], v[98:101]
	v_mfma_f32_16x16x32_bf16 v[86:89], v[148:151], v[180:183], v[86:89]
	v_mfma_f32_16x16x32_bf16 v[82:85], v[156:159], v[180:183], v[82:85]
	v_mfma_f32_16x16x32_bf16 v[70:73], v[148:151], v[188:191], v[70:73]
	v_mfma_f32_16x16x32_bf16 v[66:69], v[156:159], v[188:191], v[66:69]
	v_mfma_f32_16x16x32_bf16 v[118:121], v[152:155], v[168:171], v[118:121]
	v_mfma_f32_16x16x32_bf16 v[114:117], v[160:163], v[168:171], v[114:117]
	v_mfma_f32_16x16x32_bf16 v[102:105], v[152:155], v[176:179], v[102:105]
	v_mfma_f32_16x16x32_bf16 v[98:101], v[160:163], v[176:179], v[98:101]
	v_mfma_f32_16x16x32_bf16 v[86:89], v[152:155], v[184:187], v[86:89]
	v_mfma_f32_16x16x32_bf16 v[82:85], v[160:163], v[184:187], v[82:85]
	v_mfma_f32_16x16x32_bf16 v[70:73], v[152:155], v[212:215], v[70:73]
	v_mfma_f32_16x16x32_bf16 v[66:69], v[160:163], v[212:215], v[66:69]
	s_barrier
	s_add_u32 s20, s24, 0x158000
	s_addc_u32 s21, s25, 0
	s_add_i32 s2, s2, s0
	s_mov_b32 m0, s2
	ds_read_b128 v[164:167], v242 offset:16384
	ds_read_b128 v[168:171], v242 offset:17408
	global_load_lds_dwordx4 v0, s[24:25]
	s_add_i32 m0, s2, 0x2000
	s_add_i32 s2, s43, s0
	ds_read_b128 v[172:175], v242 offset:18432
	ds_read_b128 v[176:179], v242 offset:19456
	global_load_lds_dwordx4 v192, s[24:25]
	s_mov_b32 m0, s2
	ds_read_b128 v[180:183], v242 offset:20480
	ds_read_b128 v[184:187], v242 offset:21504
	global_load_lds_dwordx4 v0, s[20:21]
	s_add_i32 m0, s2, 0x2000
	ds_read_b128 v[188:191], v242 offset:22528
	ds_read_b128 v[212:215], v242 offset:23552
	global_load_lds_dwordx4 v192, s[20:21]
	s_waitcnt vmcnt(6)
	s_waitcnt lgkmcnt(0)
	s_barrier
	s_waitcnt lgkmcnt(0)
	v_mfma_f32_16x16x32_bf16 v[62:65], v[130:133], v[164:167], v[62:65]
	v_mfma_f32_16x16x32_bf16 v[58:61], v[138:141], v[164:167], v[58:61]
	v_mfma_f32_16x16x32_bf16 v[46:49], v[130:133], v[172:175], v[46:49]
	v_mfma_f32_16x16x32_bf16 v[42:45], v[138:141], v[172:175], v[42:45]
	v_mfma_f32_16x16x32_bf16 v[30:33], v[130:133], v[180:183], v[30:33]
	v_mfma_f32_16x16x32_bf16 v[26:29], v[138:141], v[180:183], v[26:29]
	v_mfma_f32_16x16x32_bf16 v[14:17], v[130:133], v[188:191], v[14:17]
	v_mfma_f32_16x16x32_bf16 v[10:13], v[138:141], v[188:191], v[10:13]
	v_mfma_f32_16x16x32_bf16 v[62:65], v[134:137], v[168:171], v[62:65]
	v_mfma_f32_16x16x32_bf16 v[58:61], v[142:145], v[168:171], v[58:61]
	v_mfma_f32_16x16x32_bf16 v[46:49], v[134:137], v[176:179], v[46:49]
	v_mfma_f32_16x16x32_bf16 v[42:45], v[142:145], v[176:179], v[42:45]
	v_mfma_f32_16x16x32_bf16 v[30:33], v[134:137], v[184:187], v[30:33]
	v_mfma_f32_16x16x32_bf16 v[26:29], v[142:145], v[184:187], v[26:29]
	v_mfma_f32_16x16x32_bf16 v[14:17], v[134:137], v[212:215], v[14:17]
	v_mfma_f32_16x16x32_bf16 v[10:13], v[142:145], v[212:215], v[10:13]
	v_mfma_f32_16x16x32_bf16 v[54:57], v[148:151], v[164:167], v[54:57]
	v_mfma_f32_16x16x32_bf16 v[50:53], v[156:159], v[164:167], v[50:53]
	v_mfma_f32_16x16x32_bf16 v[38:41], v[148:151], v[172:175], v[38:41]
	v_mfma_f32_16x16x32_bf16 v[34:37], v[156:159], v[172:175], v[34:37]
	v_mfma_f32_16x16x32_bf16 v[22:25], v[148:151], v[180:183], v[22:25]
	v_mfma_f32_16x16x32_bf16 v[18:21], v[156:159], v[180:183], v[18:21]
	v_mfma_f32_16x16x32_bf16 v[6:9], v[148:151], v[188:191], v[6:9]
	v_mfma_f32_16x16x32_bf16 v[2:5], v[156:159], v[188:191], v[2:5]
	v_mfma_f32_16x16x32_bf16 v[54:57], v[152:155], v[168:171], v[54:57]
	v_mfma_f32_16x16x32_bf16 v[50:53], v[160:163], v[168:171], v[50:53]
	v_mfma_f32_16x16x32_bf16 v[38:41], v[152:155], v[176:179], v[38:41]
	v_mfma_f32_16x16x32_bf16 v[34:37], v[160:163], v[176:179], v[34:37]
	v_mfma_f32_16x16x32_bf16 v[22:25], v[152:155], v[184:187], v[22:25]
	v_mfma_f32_16x16x32_bf16 v[18:21], v[160:163], v[184:187], v[18:21]
	v_mfma_f32_16x16x32_bf16 v[6:9], v[152:155], v[212:215], v[6:9]
	v_mfma_f32_16x16x32_bf16 v[2:5], v[160:163], v[212:215], v[2:5]
	s_barrier
	s_add_u32 s20, s26, 0x158000
	s_addc_u32 s21, s27, 0
	s_add_i32 s2, 0, 0x18000
	s_add_i32 s43, 0, 0x1c000
	v_add_u32_e32 v142, s2, v240
	v_add_u32_e32 v160, s43, v240
	s_mov_b32 m0, s1
	ds_read_b128 v[130:133], v142
	ds_read_b128 v[134:137], v142 offset:1024
	ds_read_b128 v[138:141], v142 offset:2048
	ds_read_b128 v[142:145], v142 offset:3072
	global_load_lds_dwordx4 v206, s[26:27]
	s_mov_b32 m0, s30
	ds_read_b128 v[148:151], v160
	ds_read_b128 v[152:155], v160 offset:1024
	ds_read_b128 v[156:159], v160 offset:2048
	ds_read_b128 v[160:163], v160 offset:3072
	global_load_lds_dwordx4 v194, s[26:27]
	s_mov_b32 m0, s31
	ds_read_b128 v[164:167], v242 offset:32768
	ds_read_b128 v[168:171], v242 offset:33792
	ds_read_b128 v[172:175], v242 offset:34816
	ds_read_b128 v[176:179], v242 offset:35840
	global_load_lds_dwordx4 v206, s[20:21]
	s_mov_b32 m0, s33
	ds_read_b128 v[180:183], v242 offset:36864
	ds_read_b128 v[184:187], v242 offset:37888
	ds_read_b128 v[188:191], v242 offset:38912
	ds_read_b128 v[212:215], v242 offset:39936
	global_load_lds_dwordx4 v194, s[20:21]
	s_waitcnt vmcnt(8)
	s_waitcnt lgkmcnt(0)
	s_barrier
	s_waitcnt lgkmcnt(0)
	v_mfma_f32_16x16x32_bf16 v[126:129], v[130:133], v[164:167], v[126:129]
	v_mfma_f32_16x16x32_bf16 v[122:125], v[138:141], v[164:167], v[122:125]
	v_mfma_f32_16x16x32_bf16 v[110:113], v[130:133], v[172:175], v[110:113]
	v_mfma_f32_16x16x32_bf16 v[106:109], v[138:141], v[172:175], v[106:109]
	v_mfma_f32_16x16x32_bf16 v[94:97], v[130:133], v[180:183], v[94:97]
	v_mfma_f32_16x16x32_bf16 v[90:93], v[138:141], v[180:183], v[90:93]
	v_mfma_f32_16x16x32_bf16 v[78:81], v[130:133], v[188:191], v[78:81]
	v_mfma_f32_16x16x32_bf16 v[74:77], v[138:141], v[188:191], v[74:77]
	v_mfma_f32_16x16x32_bf16 v[126:129], v[134:137], v[168:171], v[126:129]
	v_mfma_f32_16x16x32_bf16 v[122:125], v[142:145], v[168:171], v[122:125]
	v_mfma_f32_16x16x32_bf16 v[110:113], v[134:137], v[176:179], v[110:113]
	v_mfma_f32_16x16x32_bf16 v[106:109], v[142:145], v[176:179], v[106:109]
	v_mfma_f32_16x16x32_bf16 v[94:97], v[134:137], v[184:187], v[94:97]
	v_mfma_f32_16x16x32_bf16 v[90:93], v[142:145], v[184:187], v[90:93]
	v_mfma_f32_16x16x32_bf16 v[78:81], v[134:137], v[212:215], v[78:81]
	v_mfma_f32_16x16x32_bf16 v[74:77], v[142:145], v[212:215], v[74:77]
	v_mfma_f32_16x16x32_bf16 v[118:121], v[148:151], v[164:167], v[118:121]
	v_mfma_f32_16x16x32_bf16 v[114:117], v[156:159], v[164:167], v[114:117]
	v_mfma_f32_16x16x32_bf16 v[102:105], v[148:151], v[172:175], v[102:105]
	v_mfma_f32_16x16x32_bf16 v[98:101], v[156:159], v[172:175], v[98:101]
	v_mfma_f32_16x16x32_bf16 v[86:89], v[148:151], v[180:183], v[86:89]
	v_mfma_f32_16x16x32_bf16 v[82:85], v[156:159], v[180:183], v[82:85]
	v_mfma_f32_16x16x32_bf16 v[70:73], v[148:151], v[188:191], v[70:73]
	v_mfma_f32_16x16x32_bf16 v[66:69], v[156:159], v[188:191], v[66:69]
	v_mfma_f32_16x16x32_bf16 v[118:121], v[152:155], v[168:171], v[118:121]
	v_mfma_f32_16x16x32_bf16 v[114:117], v[160:163], v[168:171], v[114:117]
	v_mfma_f32_16x16x32_bf16 v[102:105], v[152:155], v[176:179], v[102:105]
	v_mfma_f32_16x16x32_bf16 v[98:101], v[160:163], v[176:179], v[98:101]
	v_mfma_f32_16x16x32_bf16 v[86:89], v[152:155], v[184:187], v[86:89]
	v_mfma_f32_16x16x32_bf16 v[82:85], v[160:163], v[184:187], v[82:85]
	v_mfma_f32_16x16x32_bf16 v[70:73], v[152:155], v[212:215], v[70:73]
	v_mfma_f32_16x16x32_bf16 v[66:69], v[160:163], v[212:215], v[66:69]
	s_barrier
	s_add_u32 s20, s24, 0x158080
	s_addc_u32 s21, s25, 0
	s_add_u32 s24, s24, 0x80
	s_addc_u32 s25, s25, 0
	s_add_i32 s2, s2, s0
	s_mov_b32 m0, s2
	ds_read_b128 v[164:167], v242 offset:49152
	ds_read_b128 v[168:171], v242 offset:50176
	global_load_lds_dwordx4 v0, s[24:25]
	s_add_i32 m0, s2, 0x2000
	s_add_i32 s2, s43, s0
	ds_read_b128 v[172:175], v242 offset:51200
	ds_read_b128 v[176:179], v242 offset:52224
	global_load_lds_dwordx4 v192, s[24:25]
	s_mov_b32 m0, s2
	ds_read_b128 v[180:183], v242 offset:53248
	ds_read_b128 v[184:187], v242 offset:54272
	global_load_lds_dwordx4 v0, s[20:21]
	s_add_i32 m0, s2, 0x2000
	ds_read_b128 v[188:191], v242 offset:55296
	ds_read_b128 v[212:215], v242 offset:56320
	global_load_lds_dwordx4 v192, s[20:21]
	s_waitcnt vmcnt(6)
	s_waitcnt lgkmcnt(0)
	s_barrier
	s_waitcnt lgkmcnt(0)
	v_mfma_f32_16x16x32_bf16 v[62:65], v[130:133], v[164:167], v[62:65]
	v_mfma_f32_16x16x32_bf16 v[58:61], v[138:141], v[164:167], v[58:61]
	v_mfma_f32_16x16x32_bf16 v[46:49], v[130:133], v[172:175], v[46:49]
	v_mfma_f32_16x16x32_bf16 v[42:45], v[138:141], v[172:175], v[42:45]
	v_mfma_f32_16x16x32_bf16 v[30:33], v[130:133], v[180:183], v[30:33]
	v_mfma_f32_16x16x32_bf16 v[26:29], v[138:141], v[180:183], v[26:29]
	v_mfma_f32_16x16x32_bf16 v[14:17], v[130:133], v[188:191], v[14:17]
	v_mfma_f32_16x16x32_bf16 v[10:13], v[138:141], v[188:191], v[10:13]
	v_mfma_f32_16x16x32_bf16 v[62:65], v[134:137], v[168:171], v[62:65]
	v_mfma_f32_16x16x32_bf16 v[58:61], v[142:145], v[168:171], v[58:61]
	v_mfma_f32_16x16x32_bf16 v[46:49], v[134:137], v[176:179], v[46:49]
	v_mfma_f32_16x16x32_bf16 v[42:45], v[142:145], v[176:179], v[42:45]
	v_mfma_f32_16x16x32_bf16 v[30:33], v[134:137], v[184:187], v[30:33]
	v_mfma_f32_16x16x32_bf16 v[26:29], v[142:145], v[184:187], v[26:29]
	v_mfma_f32_16x16x32_bf16 v[14:17], v[134:137], v[212:215], v[14:17]
	v_mfma_f32_16x16x32_bf16 v[10:13], v[142:145], v[212:215], v[10:13]
	v_mfma_f32_16x16x32_bf16 v[54:57], v[148:151], v[164:167], v[54:57]
	v_mfma_f32_16x16x32_bf16 v[50:53], v[156:159], v[164:167], v[50:53]
	v_mfma_f32_16x16x32_bf16 v[38:41], v[148:151], v[172:175], v[38:41]
	v_mfma_f32_16x16x32_bf16 v[34:37], v[156:159], v[172:175], v[34:37]
	v_mfma_f32_16x16x32_bf16 v[22:25], v[148:151], v[180:183], v[22:25]
	v_mfma_f32_16x16x32_bf16 v[18:21], v[156:159], v[180:183], v[18:21]
	v_mfma_f32_16x16x32_bf16 v[6:9], v[148:151], v[188:191], v[6:9]
	v_mfma_f32_16x16x32_bf16 v[2:5], v[156:159], v[188:191], v[2:5]
	v_mfma_f32_16x16x32_bf16 v[54:57], v[152:155], v[168:171], v[54:57]
	v_mfma_f32_16x16x32_bf16 v[50:53], v[160:163], v[168:171], v[50:53]
	v_mfma_f32_16x16x32_bf16 v[38:41], v[152:155], v[176:179], v[38:41]
	v_mfma_f32_16x16x32_bf16 v[34:37], v[160:163], v[176:179], v[34:37]
	v_mfma_f32_16x16x32_bf16 v[22:25], v[152:155], v[184:187], v[22:25]
	v_mfma_f32_16x16x32_bf16 v[18:21], v[160:163], v[184:187], v[18:21]
	v_mfma_f32_16x16x32_bf16 v[6:9], v[152:155], v[212:215], v[6:9]
	v_mfma_f32_16x16x32_bf16 v[2:5], v[160:163], v[212:215], v[2:5]
	s_barrier
	s_add_i32 s42, s42, 2
	s_add_u32 s40, s40, 0x100
	s_addc_u32 s41, s41, 0
	s_cmpk_gt_u32 s42, 0x53
	s_mov_b64 s[20:21], s[22:23]
	s_cbranch_scc0 .LBB0_322
	s_nop 0
	s_nop 0
	s_nop 0
	s_and_b64 vcc, exec, s[16:17]
	s_cbranch_vccz .LBB0_325
	s_barrier

.LBB0_408:
	s_add_u32 s2, s24, 0xfff80080
	s_addc_u32 s22, s25, -1
	s_add_i32 s45, 0, 0x10000
	s_cmp_eq_u32 s44, 28
	s_cselect_b32 s27, s17, s22
	s_cselect_b32 s26, s40, s2
	v_add_u32_e32 v144, s45, v148
	s_cselect_b32 s23, s15, s43
	s_cselect_b32 s22, s41, s42
	s_add_u32 s100, s24, 0xfff80000
	s_addc_u32 s101, s25, -1
	s_add_i32 s2, 0, 0x14000
	s_mov_b32 m0, s35
	ds_read_b128 v[140:143], v144
	ds_read_b128 v[152:155], v144 offset:1024
	ds_read_b128 v[156:159], v144 offset:2048
	ds_read_b128 v[160:163], v144 offset:3072
	global_load_lds_dwordx4 v136, s[100:101]
	s_mov_b32 m0, s36
	v_add_u32_e32 v144, s2, v148
	ds_read_b128 v[164:167], v144
	ds_read_b128 v[168:171], v144 offset:1024
	ds_read_b128 v[172:175], v144 offset:2048
	ds_read_b128 v[176:179], v144 offset:3072
	global_load_lds_dwordx4 v138, s[100:101]
	s_add_i32 m0, s29, 0xc000
	ds_read_b128 v[180:183], v151
	ds_read_b128 v[184:187], v151 offset:1024
	ds_read_b128 v[188:191], v151 offset:2048
	ds_read_b128 v[192:195], v151 offset:3072
	global_load_lds_dwordx4 v136, s[24:25]
	s_add_i32 m0, s29, 0xe000
	ds_read_b128 v[206:209], v151 offset:4096
	ds_read_b128 v[210:213], v151 offset:5120
	ds_read_b128 v[214:217], v151 offset:6144
	ds_read_b128 v[218:221], v151 offset:7168
	global_load_lds_dwordx4 v138, s[24:25]
	s_waitcnt vmcnt(8)
	s_waitcnt lgkmcnt(0)
	s_barrier
	s_waitcnt lgkmcnt(0)
	v_mfma_f32_16x16x32_bf16 v[126:129], v[140:143], v[180:183], v[126:129]
	v_mfma_f32_16x16x32_bf16 v[122:125], v[156:159], v[180:183], v[122:125]
	v_mfma_f32_16x16x32_bf16 v[110:113], v[140:143], v[188:191], v[110:113]
	v_mfma_f32_16x16x32_bf16 v[106:109], v[156:159], v[188:191], v[106:109]
	v_mfma_f32_16x16x32_bf16 v[94:97], v[140:143], v[206:209], v[94:97]
	v_mfma_f32_16x16x32_bf16 v[90:93], v[156:159], v[206:209], v[90:93]
	v_mfma_f32_16x16x32_bf16 v[78:81], v[140:143], v[214:217], v[78:81]
	v_mfma_f32_16x16x32_bf16 v[74:77], v[156:159], v[214:217], v[74:77]
	v_mfma_f32_16x16x32_bf16 v[126:129], v[152:155], v[184:187], v[126:129]
	v_mfma_f32_16x16x32_bf16 v[122:125], v[160:163], v[184:187], v[122:125]
	v_mfma_f32_16x16x32_bf16 v[110:113], v[152:155], v[192:195], v[110:113]
	v_mfma_f32_16x16x32_bf16 v[106:109], v[160:163], v[192:195], v[106:109]
	v_mfma_f32_16x16x32_bf16 v[94:97], v[152:155], v[210:213], v[94:97]
	v_mfma_f32_16x16x32_bf16 v[90:93], v[160:163], v[210:213], v[90:93]
	v_mfma_f32_16x16x32_bf16 v[78:81], v[152:155], v[218:221], v[78:81]
	v_mfma_f32_16x16x32_bf16 v[74:77], v[160:163], v[218:221], v[74:77]
	v_mfma_f32_16x16x32_bf16 v[118:121], v[164:167], v[180:183], v[118:121]
	v_mfma_f32_16x16x32_bf16 v[114:117], v[172:175], v[180:183], v[114:117]
	v_mfma_f32_16x16x32_bf16 v[102:105], v[164:167], v[188:191], v[102:105]
	v_mfma_f32_16x16x32_bf16 v[98:101], v[172:175], v[188:191], v[98:101]
	v_mfma_f32_16x16x32_bf16 v[86:89], v[164:167], v[206:209], v[86:89]
	v_mfma_f32_16x16x32_bf16 v[82:85], v[172:175], v[206:209], v[82:85]
	v_mfma_f32_16x16x32_bf16 v[70:73], v[164:167], v[214:217], v[70:73]
	v_mfma_f32_16x16x32_bf16 v[66:69], v[172:175], v[214:217], v[66:69]
	v_mfma_f32_16x16x32_bf16 v[118:121], v[168:171], v[184:187], v[118:121]
	v_mfma_f32_16x16x32_bf16 v[114:117], v[176:179], v[184:187], v[114:117]
	v_mfma_f32_16x16x32_bf16 v[102:105], v[168:171], v[192:195], v[102:105]
	v_mfma_f32_16x16x32_bf16 v[98:101], v[176:179], v[192:195], v[98:101]
	v_mfma_f32_16x16x32_bf16 v[86:89], v[168:171], v[210:213], v[86:89]
	v_mfma_f32_16x16x32_bf16 v[82:85], v[176:179], v[210:213], v[82:85]
	v_mfma_f32_16x16x32_bf16 v[70:73], v[168:171], v[218:221], v[70:73]
	v_mfma_f32_16x16x32_bf16 v[66:69], v[176:179], v[218:221], v[66:69]
	s_barrier
	s_add_u32 s46, s22, 0x80000
	s_addc_u32 s47, s23, 0
	s_add_i32 s45, s45, s28
	s_mov_b32 m0, s45
	ds_read_b128 v[180:183], v151 offset:16384
	ds_read_b128 v[184:187], v151 offset:17408
	global_load_lds_dwordx4 v0, s[22:23]
	s_add_i32 m0, s45, 0x2000
	s_add_i32 s2, s2, s28
	ds_read_b128 v[188:191], v151 offset:18432
	ds_read_b128 v[192:195], v151 offset:19456
	global_load_lds_dwordx4 v130, s[22:23]
	s_mov_b32 m0, s2
	ds_read_b128 v[206:209], v151 offset:20480
	ds_read_b128 v[210:213], v151 offset:21504
	global_load_lds_dwordx4 v0, s[46:47]
	s_add_i32 m0, s2, 0x2000
	ds_read_b128 v[214:217], v151 offset:22528
	ds_read_b128 v[218:221], v151 offset:23552
	global_load_lds_dwordx4 v130, s[46:47]
	s_waitcnt vmcnt(6)
	s_waitcnt lgkmcnt(0)
	s_barrier
	s_waitcnt lgkmcnt(0)
	v_mfma_f32_16x16x32_bf16 v[62:65], v[140:143], v[180:183], v[62:65]
	v_mfma_f32_16x16x32_bf16 v[58:61], v[156:159], v[180:183], v[58:61]
	v_mfma_f32_16x16x32_bf16 v[46:49], v[140:143], v[188:191], v[46:49]
	v_mfma_f32_16x16x32_bf16 v[42:45], v[156:159], v[188:191], v[42:45]
	v_mfma_f32_16x16x32_bf16 v[30:33], v[140:143], v[206:209], v[30:33]
	v_mfma_f32_16x16x32_bf16 v[26:29], v[156:159], v[206:209], v[26:29]
	v_mfma_f32_16x16x32_bf16 v[14:17], v[140:143], v[214:217], v[14:17]
	v_mfma_f32_16x16x32_bf16 v[10:13], v[156:159], v[214:217], v[10:13]
	v_mfma_f32_16x16x32_bf16 v[62:65], v[152:155], v[184:187], v[62:65]
	v_mfma_f32_16x16x32_bf16 v[58:61], v[160:163], v[184:187], v[58:61]
	v_mfma_f32_16x16x32_bf16 v[46:49], v[152:155], v[192:195], v[46:49]
	v_mfma_f32_16x16x32_bf16 v[42:45], v[160:163], v[192:195], v[42:45]
	v_mfma_f32_16x16x32_bf16 v[30:33], v[152:155], v[210:213], v[30:33]
	v_mfma_f32_16x16x32_bf16 v[26:29], v[160:163], v[210:213], v[26:29]
	v_mfma_f32_16x16x32_bf16 v[14:17], v[152:155], v[218:221], v[14:17]
	v_mfma_f32_16x16x32_bf16 v[10:13], v[160:163], v[218:221], v[10:13]
	v_mfma_f32_16x16x32_bf16 v[54:57], v[164:167], v[180:183], v[54:57]
	v_mfma_f32_16x16x32_bf16 v[50:53], v[172:175], v[180:183], v[50:53]
	v_mfma_f32_16x16x32_bf16 v[38:41], v[164:167], v[188:191], v[38:41]
	v_mfma_f32_16x16x32_bf16 v[34:37], v[172:175], v[188:191], v[34:37]
	v_mfma_f32_16x16x32_bf16 v[22:25], v[164:167], v[206:209], v[22:25]
	v_mfma_f32_16x16x32_bf16 v[18:21], v[172:175], v[206:209], v[18:21]
	v_mfma_f32_16x16x32_bf16 v[6:9], v[164:167], v[214:217], v[6:9]
	v_mfma_f32_16x16x32_bf16 v[2:5], v[172:175], v[214:217], v[2:5]
	v_mfma_f32_16x16x32_bf16 v[54:57], v[168:171], v[184:187], v[54:57]
	v_mfma_f32_16x16x32_bf16 v[50:53], v[176:179], v[184:187], v[50:53]
	v_mfma_f32_16x16x32_bf16 v[38:41], v[168:171], v[192:195], v[38:41]
	v_mfma_f32_16x16x32_bf16 v[34:37], v[176:179], v[192:195], v[34:37]
	v_mfma_f32_16x16x32_bf16 v[22:25], v[168:171], v[210:213], v[22:25]
	v_mfma_f32_16x16x32_bf16 v[18:21], v[176:179], v[210:213], v[18:21]
	v_mfma_f32_16x16x32_bf16 v[6:9], v[168:171], v[218:221], v[6:9]
	v_mfma_f32_16x16x32_bf16 v[2:5], v[176:179], v[218:221], v[2:5]
	s_barrier
	s_add_u32 s26, s26, 0x80000
	s_addc_u32 s27, s27, 0
	s_add_u32 s100, s26, 0xfff80000
	s_addc_u32 s101, s27, -1
	s_add_i32 s2, 0, 0x18000
	s_add_i32 s45, 0, 0x1c000
	v_add_u32_e32 v160, s2, v148
	v_add_u32_e32 v176, s45, v148
	s_mov_b32 m0, s29
	ds_read_b128 v[140:143], v160
	ds_read_b128 v[152:155], v160 offset:1024
	ds_read_b128 v[156:159], v160 offset:2048
	ds_read_b128 v[160:163], v160 offset:3072
	global_load_lds_dwordx4 v134, s[100:101]
	s_mov_b32 m0, s30
	ds_read_b128 v[164:167], v176
	ds_read_b128 v[168:171], v176 offset:1024
	ds_read_b128 v[172:175], v176 offset:2048
	ds_read_b128 v[176:179], v176 offset:3072
	global_load_lds_dwordx4 v132, s[100:101]
	s_mov_b32 m0, s31
	ds_read_b128 v[180:183], v151 offset:32768
	ds_read_b128 v[184:187], v151 offset:33792
	ds_read_b128 v[188:191], v151 offset:34816
	ds_read_b128 v[192:195], v151 offset:35840
	global_load_lds_dwordx4 v134, s[26:27]
	s_mov_b32 m0, s33
	ds_read_b128 v[206:209], v151 offset:36864
	ds_read_b128 v[210:213], v151 offset:37888
	ds_read_b128 v[214:217], v151 offset:38912
	ds_read_b128 v[218:221], v151 offset:39936
	global_load_lds_dwordx4 v132, s[26:27]
	s_waitcnt vmcnt(8)
	s_waitcnt lgkmcnt(0)
	s_barrier
	s_waitcnt lgkmcnt(0)
	v_mfma_f32_16x16x32_bf16 v[126:129], v[140:143], v[180:183], v[126:129]
	v_mfma_f32_16x16x32_bf16 v[122:125], v[156:159], v[180:183], v[122:125]
	v_mfma_f32_16x16x32_bf16 v[110:113], v[140:143], v[188:191], v[110:113]
	v_mfma_f32_16x16x32_bf16 v[106:109], v[156:159], v[188:191], v[106:109]
	v_mfma_f32_16x16x32_bf16 v[94:97], v[140:143], v[206:209], v[94:97]
	v_mfma_f32_16x16x32_bf16 v[90:93], v[156:159], v[206:209], v[90:93]
	v_mfma_f32_16x16x32_bf16 v[78:81], v[140:143], v[214:217], v[78:81]
	v_mfma_f32_16x16x32_bf16 v[74:77], v[156:159], v[214:217], v[74:77]
	v_mfma_f32_16x16x32_bf16 v[126:129], v[152:155], v[184:187], v[126:129]
	v_mfma_f32_16x16x32_bf16 v[122:125], v[160:163], v[184:187], v[122:125]
	v_mfma_f32_16x16x32_bf16 v[110:113], v[152:155], v[192:195], v[110:113]
	v_mfma_f32_16x16x32_bf16 v[106:109], v[160:163], v[192:195], v[106:109]
	v_mfma_f32_16x16x32_bf16 v[94:97], v[152:155], v[210:213], v[94:97]
	v_mfma_f32_16x16x32_bf16 v[90:93], v[160:163], v[210:213], v[90:93]
	v_mfma_f32_16x16x32_bf16 v[78:81], v[152:155], v[218:221], v[78:81]
	v_mfma_f32_16x16x32_bf16 v[74:77], v[160:163], v[218:221], v[74:77]
	v_mfma_f32_16x16x32_bf16 v[118:121], v[164:167], v[180:183], v[118:121]
	v_mfma_f32_16x16x32_bf16 v[114:117], v[172:175], v[180:183], v[114:117]
	v_mfma_f32_16x16x32_bf16 v[102:105], v[164:167], v[188:191], v[102:105]
	v_mfma_f32_16x16x32_bf16 v[98:101], v[172:175], v[188:191], v[98:101]
	v_mfma_f32_16x16x32_bf16 v[86:89], v[164:167], v[206:209], v[86:89]
	v_mfma_f32_16x16x32_bf16 v[82:85], v[172:175], v[206:209], v[82:85]
	v_mfma_f32_16x16x32_bf16 v[70:73], v[164:167], v[214:217], v[70:73]
	v_mfma_f32_16x16x32_bf16 v[66:69], v[172:175], v[214:217], v[66:69]
	v_mfma_f32_16x16x32_bf16 v[118:121], v[168:171], v[184:187], v[118:121]
	v_mfma_f32_16x16x32_bf16 v[114:117], v[176:179], v[184:187], v[114:117]
	v_mfma_f32_16x16x32_bf16 v[102:105], v[168:171], v[192:195], v[102:105]
	v_mfma_f32_16x16x32_bf16 v[98:101], v[176:179], v[192:195], v[98:101]
	v_mfma_f32_16x16x32_bf16 v[86:89], v[168:171], v[210:213], v[86:89]
	v_mfma_f32_16x16x32_bf16 v[82:85], v[176:179], v[210:213], v[82:85]
	v_mfma_f32_16x16x32_bf16 v[70:73], v[168:171], v[218:221], v[70:73]
	v_mfma_f32_16x16x32_bf16 v[66:69], v[176:179], v[218:221], v[66:69]
	s_barrier
	s_add_u32 s22, s22, 0x80080
	s_addc_u32 s23, s23, 0
	s_add_u32 s46, s46, 0xfff80080
	s_addc_u32 s47, s47, -1
	s_add_i32 s2, s2, s28
	s_mov_b32 m0, s2
	ds_read_b128 v[180:183], v151 offset:49152
	ds_read_b128 v[184:187], v151 offset:50176
	global_load_lds_dwordx4 v0, s[46:47]
	s_add_i32 m0, s2, 0x2000
	s_add_i32 s2, s45, s28
	ds_read_b128 v[188:191], v151 offset:51200
	ds_read_b128 v[192:195], v151 offset:52224
	global_load_lds_dwordx4 v130, s[46:47]
	s_mov_b32 m0, s2
	ds_read_b128 v[206:209], v151 offset:53248
	ds_read_b128 v[210:213], v151 offset:54272
	global_load_lds_dwordx4 v0, s[22:23]
	s_add_i32 m0, s2, 0x2000
	ds_read_b128 v[214:217], v151 offset:55296
	ds_read_b128 v[218:221], v151 offset:56320
	global_load_lds_dwordx4 v130, s[22:23]
	s_waitcnt vmcnt(6)
	s_waitcnt lgkmcnt(0)
	s_barrier
	s_waitcnt lgkmcnt(0)
	v_mfma_f32_16x16x32_bf16 v[62:65], v[140:143], v[180:183], v[62:65]
	v_mfma_f32_16x16x32_bf16 v[58:61], v[156:159], v[180:183], v[58:61]
	v_mfma_f32_16x16x32_bf16 v[46:49], v[140:143], v[188:191], v[46:49]
	v_mfma_f32_16x16x32_bf16 v[42:45], v[156:159], v[188:191], v[42:45]
	v_mfma_f32_16x16x32_bf16 v[30:33], v[140:143], v[206:209], v[30:33]
	v_mfma_f32_16x16x32_bf16 v[26:29], v[156:159], v[206:209], v[26:29]
	v_mfma_f32_16x16x32_bf16 v[14:17], v[140:143], v[214:217], v[14:17]
	v_mfma_f32_16x16x32_bf16 v[10:13], v[156:159], v[214:217], v[10:13]
	v_mfma_f32_16x16x32_bf16 v[62:65], v[152:155], v[184:187], v[62:65]
	v_mfma_f32_16x16x32_bf16 v[58:61], v[160:163], v[184:187], v[58:61]
	v_mfma_f32_16x16x32_bf16 v[46:49], v[152:155], v[192:195], v[46:49]
	v_mfma_f32_16x16x32_bf16 v[42:45], v[160:163], v[192:195], v[42:45]
	v_mfma_f32_16x16x32_bf16 v[30:33], v[152:155], v[210:213], v[30:33]
	v_mfma_f32_16x16x32_bf16 v[26:29], v[160:163], v[210:213], v[26:29]
	v_mfma_f32_16x16x32_bf16 v[14:17], v[152:155], v[218:221], v[14:17]
	v_mfma_f32_16x16x32_bf16 v[10:13], v[160:163], v[218:221], v[10:13]
	v_mfma_f32_16x16x32_bf16 v[54:57], v[164:167], v[180:183], v[54:57]
	v_mfma_f32_16x16x32_bf16 v[50:53], v[172:175], v[180:183], v[50:53]
	v_mfma_f32_16x16x32_bf16 v[38:41], v[164:167], v[188:191], v[38:41]
	v_mfma_f32_16x16x32_bf16 v[34:37], v[172:175], v[188:191], v[34:37]
	v_mfma_f32_16x16x32_bf16 v[22:25], v[164:167], v[206:209], v[22:25]
	v_mfma_f32_16x16x32_bf16 v[18:21], v[172:175], v[206:209], v[18:21]
	v_mfma_f32_16x16x32_bf16 v[6:9], v[164:167], v[214:217], v[6:9]
	v_mfma_f32_16x16x32_bf16 v[2:5], v[172:175], v[214:217], v[2:5]
	v_mfma_f32_16x16x32_bf16 v[54:57], v[168:171], v[184:187], v[54:57]
	v_mfma_f32_16x16x32_bf16 v[50:53], v[176:179], v[184:187], v[50:53]
	v_mfma_f32_16x16x32_bf16 v[38:41], v[168:171], v[192:195], v[38:41]
	v_mfma_f32_16x16x32_bf16 v[34:37], v[176:179], v[192:195], v[34:37]
	v_mfma_f32_16x16x32_bf16 v[22:25], v[168:171], v[210:213], v[22:25]
	v_mfma_f32_16x16x32_bf16 v[18:21], v[176:179], v[210:213], v[18:21]
	v_mfma_f32_16x16x32_bf16 v[6:9], v[168:171], v[218:221], v[6:9]
	v_mfma_f32_16x16x32_bf16 v[2:5], v[176:179], v[218:221], v[2:5]
	s_barrier
	s_add_i32 s44, s44, 2
	s_add_u32 s24, s24, 0x100
	s_addc_u32 s25, s25, 0
	s_add_u32 s42, s42, 0x100
	s_addc_u32 s43, s43, 0
	s_cmp_gt_u32 s44, 29
	s_cbranch_scc0 .LBB0_408
	s_and_b64 vcc, exec, s[12:13]
	s_cbranch_vccz .LBB0_411
	s_barrier

.LBB0_440:
	s_add_u32 s2, s18, 0xfff80080
	s_addc_u32 s10, s19, -1
	s_add_i32 s47, 0, 0x10000
	s_cmp_eq_u32 s46, 28
	s_cselect_b32 s29, s25, s10
	s_cselect_b32 s28, s34, s2
	s_cselect_b32 s11, s23, s45
	s_cselect_b32 s10, s43, s44
	s_add_u32 s100, s18, 0xfff80000
	s_addc_u32 s101, s19, -1
	s_add_i32 s2, 0, 0x14000
	v_add_u32_e32 v154, s47, v162
	v_add_u32_e32 v184, s2, v162
	s_mov_b32 m0, s38
	ds_read_b128 v[130:133], v154
	ds_read_b128 v[134:137], v154 offset:1024
	ds_read_b128 v[150:153], v154 offset:2048
	ds_read_b128 v[154:157], v154 offset:3072
	global_load_lds_dwordx4 v144, s[100:101]
	s_mov_b32 m0, s39
	ds_read_b128 v[158:161], v184
	ds_read_b128 v[176:179], v184 offset:1024
	ds_read_b128 v[180:183], v184 offset:2048
	ds_read_b128 v[184:187], v184 offset:3072
	global_load_lds_dwordx4 v148, s[100:101]
	s_add_i32 m0, s31, 0xc000
	ds_read_b128 v[188:191], v175
	ds_read_b128 v[192:195], v175 offset:1024
	ds_read_b128 v[206:209], v175 offset:2048
	ds_read_b128 v[210:213], v175 offset:3072
	global_load_lds_dwordx4 v144, s[18:19]
	s_add_i32 m0, s31, 0xe000
	ds_read_b128 v[214:217], v175 offset:4096
	ds_read_b128 v[218:221], v175 offset:5120
	ds_read_b128 v[222:225], v175 offset:6144
	ds_read_b128 v[226:229], v175 offset:7168
	global_load_lds_dwordx4 v148, s[18:19]
	s_waitcnt vmcnt(8)
	s_waitcnt lgkmcnt(0)
	s_barrier
	s_waitcnt lgkmcnt(0)
	v_mfma_f32_16x16x32_bf16 v[126:129], v[130:133], v[188:191], v[126:129]
	v_mfma_f32_16x16x32_bf16 v[122:125], v[150:153], v[188:191], v[122:125]
	v_mfma_f32_16x16x32_bf16 v[110:113], v[130:133], v[206:209], v[110:113]
	v_mfma_f32_16x16x32_bf16 v[106:109], v[150:153], v[206:209], v[106:109]
	v_mfma_f32_16x16x32_bf16 v[94:97], v[130:133], v[214:217], v[94:97]
	v_mfma_f32_16x16x32_bf16 v[90:93], v[150:153], v[214:217], v[90:93]
	v_mfma_f32_16x16x32_bf16 v[78:81], v[130:133], v[222:225], v[78:81]
	v_mfma_f32_16x16x32_bf16 v[74:77], v[150:153], v[222:225], v[74:77]
	v_mfma_f32_16x16x32_bf16 v[126:129], v[134:137], v[192:195], v[126:129]
	v_mfma_f32_16x16x32_bf16 v[122:125], v[154:157], v[192:195], v[122:125]
	v_mfma_f32_16x16x32_bf16 v[110:113], v[134:137], v[210:213], v[110:113]
	v_mfma_f32_16x16x32_bf16 v[106:109], v[154:157], v[210:213], v[106:109]
	v_mfma_f32_16x16x32_bf16 v[94:97], v[134:137], v[218:221], v[94:97]
	v_mfma_f32_16x16x32_bf16 v[90:93], v[154:157], v[218:221], v[90:93]
	v_mfma_f32_16x16x32_bf16 v[78:81], v[134:137], v[226:229], v[78:81]
	v_mfma_f32_16x16x32_bf16 v[74:77], v[154:157], v[226:229], v[74:77]
	v_mfma_f32_16x16x32_bf16 v[118:121], v[158:161], v[188:191], v[118:121]
	v_mfma_f32_16x16x32_bf16 v[114:117], v[180:183], v[188:191], v[114:117]
	v_mfma_f32_16x16x32_bf16 v[102:105], v[158:161], v[206:209], v[102:105]
	v_mfma_f32_16x16x32_bf16 v[98:101], v[180:183], v[206:209], v[98:101]
	v_mfma_f32_16x16x32_bf16 v[86:89], v[158:161], v[214:217], v[86:89]
	v_mfma_f32_16x16x32_bf16 v[82:85], v[180:183], v[214:217], v[82:85]
	v_mfma_f32_16x16x32_bf16 v[70:73], v[158:161], v[222:225], v[70:73]
	v_mfma_f32_16x16x32_bf16 v[66:69], v[180:183], v[222:225], v[66:69]
	v_mfma_f32_16x16x32_bf16 v[118:121], v[176:179], v[192:195], v[118:121]
	v_mfma_f32_16x16x32_bf16 v[114:117], v[184:187], v[192:195], v[114:117]
	v_mfma_f32_16x16x32_bf16 v[102:105], v[176:179], v[210:213], v[102:105]
	v_mfma_f32_16x16x32_bf16 v[98:101], v[184:187], v[210:213], v[98:101]
	v_mfma_f32_16x16x32_bf16 v[86:89], v[176:179], v[218:221], v[86:89]
	v_mfma_f32_16x16x32_bf16 v[82:85], v[184:187], v[218:221], v[82:85]
	v_mfma_f32_16x16x32_bf16 v[70:73], v[176:179], v[226:229], v[70:73]
	v_mfma_f32_16x16x32_bf16 v[66:69], v[184:187], v[226:229], v[66:69]
	s_barrier
	s_add_u32 s52, s10, 0x80000
	s_addc_u32 s53, s11, 0
	s_add_i32 s47, s47, s30
	s_mov_b32 m0, s47
	ds_read_b128 v[188:191], v175 offset:16384
	ds_read_b128 v[192:195], v175 offset:17408
	global_load_lds_dwordx4 v0, s[10:11]
	s_add_i32 m0, s47, 0x2000
	s_add_i32 s2, s2, s30
	ds_read_b128 v[206:209], v175 offset:18432
	ds_read_b128 v[210:213], v175 offset:19456
	global_load_lds_dwordx4 v138, s[10:11]
	s_mov_b32 m0, s2
	ds_read_b128 v[214:217], v175 offset:20480
	ds_read_b128 v[218:221], v175 offset:21504
	global_load_lds_dwordx4 v0, s[52:53]
	s_add_i32 m0, s2, 0x2000
	ds_read_b128 v[222:225], v175 offset:22528
	ds_read_b128 v[226:229], v175 offset:23552
	global_load_lds_dwordx4 v138, s[52:53]
	s_waitcnt vmcnt(6)
	s_waitcnt lgkmcnt(0)
	s_barrier
	s_waitcnt lgkmcnt(0)
	v_mfma_f32_16x16x32_bf16 v[62:65], v[130:133], v[188:191], v[62:65]
	v_mfma_f32_16x16x32_bf16 v[58:61], v[150:153], v[188:191], v[58:61]
	v_mfma_f32_16x16x32_bf16 v[46:49], v[130:133], v[206:209], v[46:49]
	v_mfma_f32_16x16x32_bf16 v[42:45], v[150:153], v[206:209], v[42:45]
	v_mfma_f32_16x16x32_bf16 v[30:33], v[130:133], v[214:217], v[30:33]
	v_mfma_f32_16x16x32_bf16 v[26:29], v[150:153], v[214:217], v[26:29]
	v_mfma_f32_16x16x32_bf16 v[14:17], v[130:133], v[222:225], v[14:17]
	v_mfma_f32_16x16x32_bf16 v[10:13], v[150:153], v[222:225], v[10:13]
	v_mfma_f32_16x16x32_bf16 v[62:65], v[134:137], v[192:195], v[62:65]
	v_mfma_f32_16x16x32_bf16 v[58:61], v[154:157], v[192:195], v[58:61]
	v_mfma_f32_16x16x32_bf16 v[46:49], v[134:137], v[210:213], v[46:49]
	v_mfma_f32_16x16x32_bf16 v[42:45], v[154:157], v[210:213], v[42:45]
	v_mfma_f32_16x16x32_bf16 v[30:33], v[134:137], v[218:221], v[30:33]
	v_mfma_f32_16x16x32_bf16 v[26:29], v[154:157], v[218:221], v[26:29]
	v_mfma_f32_16x16x32_bf16 v[14:17], v[134:137], v[226:229], v[14:17]
	v_mfma_f32_16x16x32_bf16 v[10:13], v[154:157], v[226:229], v[10:13]
	v_mfma_f32_16x16x32_bf16 v[54:57], v[158:161], v[188:191], v[54:57]
	v_mfma_f32_16x16x32_bf16 v[50:53], v[180:183], v[188:191], v[50:53]
	v_mfma_f32_16x16x32_bf16 v[38:41], v[158:161], v[206:209], v[38:41]
	v_mfma_f32_16x16x32_bf16 v[34:37], v[180:183], v[206:209], v[34:37]
	v_mfma_f32_16x16x32_bf16 v[22:25], v[158:161], v[214:217], v[22:25]
	v_mfma_f32_16x16x32_bf16 v[18:21], v[180:183], v[214:217], v[18:21]
	v_mfma_f32_16x16x32_bf16 v[6:9], v[158:161], v[222:225], v[6:9]
	v_mfma_f32_16x16x32_bf16 v[2:5], v[180:183], v[222:225], v[2:5]
	v_mfma_f32_16x16x32_bf16 v[54:57], v[176:179], v[192:195], v[54:57]
	v_mfma_f32_16x16x32_bf16 v[50:53], v[184:187], v[192:195], v[50:53]
	v_mfma_f32_16x16x32_bf16 v[38:41], v[176:179], v[210:213], v[38:41]
	v_mfma_f32_16x16x32_bf16 v[34:37], v[184:187], v[210:213], v[34:37]
	v_mfma_f32_16x16x32_bf16 v[22:25], v[176:179], v[218:221], v[22:25]
	v_mfma_f32_16x16x32_bf16 v[18:21], v[184:187], v[218:221], v[18:21]
	v_mfma_f32_16x16x32_bf16 v[6:9], v[176:179], v[226:229], v[6:9]
	v_mfma_f32_16x16x32_bf16 v[2:5], v[184:187], v[226:229], v[2:5]
	s_barrier
	s_add_u32 s28, s28, 0x80000
	s_addc_u32 s29, s29, 0
	s_add_u32 s100, s28, 0xfff80000
	s_addc_u32 s101, s29, -1
	s_add_i32 s2, 0, 0x18000
	s_add_i32 s47, 0, 0x1c000
	v_add_u32_e32 v154, s2, v162
	v_add_u32_e32 v184, s47, v162
	s_mov_b32 m0, s31
	ds_read_b128 v[130:133], v154
	ds_read_b128 v[134:137], v154 offset:1024
	ds_read_b128 v[150:153], v154 offset:2048
	ds_read_b128 v[154:157], v154 offset:3072
	global_load_lds_dwordx4 v142, s[100:101]
	s_mov_b32 m0, s35
	ds_read_b128 v[158:161], v184
	ds_read_b128 v[176:179], v184 offset:1024
	ds_read_b128 v[180:183], v184 offset:2048
	ds_read_b128 v[184:187], v184 offset:3072
	global_load_lds_dwordx4 v140, s[100:101]
	s_mov_b32 m0, s36
	ds_read_b128 v[188:191], v175 offset:32768
	ds_read_b128 v[192:195], v175 offset:33792
	ds_read_b128 v[206:209], v175 offset:34816
	ds_read_b128 v[210:213], v175 offset:35840
	global_load_lds_dwordx4 v142, s[28:29]
	s_mov_b32 m0, s37
	ds_read_b128 v[214:217], v175 offset:36864
	ds_read_b128 v[218:221], v175 offset:37888
	ds_read_b128 v[222:225], v175 offset:38912
	ds_read_b128 v[226:229], v175 offset:39936
	global_load_lds_dwordx4 v140, s[28:29]
	s_waitcnt vmcnt(8)
	s_waitcnt lgkmcnt(0)
	s_barrier
	s_waitcnt lgkmcnt(0)
	v_mfma_f32_16x16x32_bf16 v[126:129], v[130:133], v[188:191], v[126:129]
	v_mfma_f32_16x16x32_bf16 v[122:125], v[150:153], v[188:191], v[122:125]
	v_mfma_f32_16x16x32_bf16 v[110:113], v[130:133], v[206:209], v[110:113]
	v_mfma_f32_16x16x32_bf16 v[106:109], v[150:153], v[206:209], v[106:109]
	v_mfma_f32_16x16x32_bf16 v[94:97], v[130:133], v[214:217], v[94:97]
	v_mfma_f32_16x16x32_bf16 v[90:93], v[150:153], v[214:217], v[90:93]
	v_mfma_f32_16x16x32_bf16 v[78:81], v[130:133], v[222:225], v[78:81]
	v_mfma_f32_16x16x32_bf16 v[74:77], v[150:153], v[222:225], v[74:77]
	v_mfma_f32_16x16x32_bf16 v[126:129], v[134:137], v[192:195], v[126:129]
	v_mfma_f32_16x16x32_bf16 v[122:125], v[154:157], v[192:195], v[122:125]
	v_mfma_f32_16x16x32_bf16 v[110:113], v[134:137], v[210:213], v[110:113]
	v_mfma_f32_16x16x32_bf16 v[106:109], v[154:157], v[210:213], v[106:109]
	v_mfma_f32_16x16x32_bf16 v[94:97], v[134:137], v[218:221], v[94:97]
	v_mfma_f32_16x16x32_bf16 v[90:93], v[154:157], v[218:221], v[90:93]
	v_mfma_f32_16x16x32_bf16 v[78:81], v[134:137], v[226:229], v[78:81]
	v_mfma_f32_16x16x32_bf16 v[74:77], v[154:157], v[226:229], v[74:77]
	v_mfma_f32_16x16x32_bf16 v[118:121], v[158:161], v[188:191], v[118:121]
	v_mfma_f32_16x16x32_bf16 v[114:117], v[180:183], v[188:191], v[114:117]
	v_mfma_f32_16x16x32_bf16 v[102:105], v[158:161], v[206:209], v[102:105]
	v_mfma_f32_16x16x32_bf16 v[98:101], v[180:183], v[206:209], v[98:101]
	v_mfma_f32_16x16x32_bf16 v[86:89], v[158:161], v[214:217], v[86:89]
	v_mfma_f32_16x16x32_bf16 v[82:85], v[180:183], v[214:217], v[82:85]
	v_mfma_f32_16x16x32_bf16 v[70:73], v[158:161], v[222:225], v[70:73]
	v_mfma_f32_16x16x32_bf16 v[66:69], v[180:183], v[222:225], v[66:69]
	v_mfma_f32_16x16x32_bf16 v[118:121], v[176:179], v[192:195], v[118:121]
	v_mfma_f32_16x16x32_bf16 v[114:117], v[184:187], v[192:195], v[114:117]
	v_mfma_f32_16x16x32_bf16 v[102:105], v[176:179], v[210:213], v[102:105]
	v_mfma_f32_16x16x32_bf16 v[98:101], v[184:187], v[210:213], v[98:101]
	v_mfma_f32_16x16x32_bf16 v[86:89], v[176:179], v[218:221], v[86:89]
	v_mfma_f32_16x16x32_bf16 v[82:85], v[184:187], v[218:221], v[82:85]
	v_mfma_f32_16x16x32_bf16 v[70:73], v[176:179], v[226:229], v[70:73]
	v_mfma_f32_16x16x32_bf16 v[66:69], v[184:187], v[226:229], v[66:69]
	s_barrier
	s_add_u32 s10, s10, 0x80080
	s_addc_u32 s11, s11, 0
	s_add_u32 s52, s52, 0xfff80080
	s_addc_u32 s53, s53, -1
	s_add_i32 s2, s2, s30
	s_mov_b32 m0, s2
	ds_read_b128 v[188:191], v175 offset:49152
	ds_read_b128 v[192:195], v175 offset:50176
	global_load_lds_dwordx4 v0, s[52:53]
	s_add_i32 m0, s2, 0x2000
	s_add_i32 s2, s47, s30
	ds_read_b128 v[206:209], v175 offset:51200
	ds_read_b128 v[210:213], v175 offset:52224
	global_load_lds_dwordx4 v138, s[52:53]
	s_mov_b32 m0, s2
	ds_read_b128 v[214:217], v175 offset:53248
	ds_read_b128 v[218:221], v175 offset:54272
	global_load_lds_dwordx4 v0, s[10:11]
	s_add_i32 m0, s2, 0x2000
	ds_read_b128 v[222:225], v175 offset:55296
	ds_read_b128 v[226:229], v175 offset:56320
	global_load_lds_dwordx4 v138, s[10:11]
	s_waitcnt vmcnt(6)
	s_waitcnt lgkmcnt(0)
	s_barrier
	s_waitcnt lgkmcnt(0)
	v_mfma_f32_16x16x32_bf16 v[62:65], v[130:133], v[188:191], v[62:65]
	v_mfma_f32_16x16x32_bf16 v[58:61], v[150:153], v[188:191], v[58:61]
	v_mfma_f32_16x16x32_bf16 v[46:49], v[130:133], v[206:209], v[46:49]
	v_mfma_f32_16x16x32_bf16 v[42:45], v[150:153], v[206:209], v[42:45]
	v_mfma_f32_16x16x32_bf16 v[30:33], v[130:133], v[214:217], v[30:33]
	v_mfma_f32_16x16x32_bf16 v[26:29], v[150:153], v[214:217], v[26:29]
	v_mfma_f32_16x16x32_bf16 v[14:17], v[130:133], v[222:225], v[14:17]
	v_mfma_f32_16x16x32_bf16 v[10:13], v[150:153], v[222:225], v[10:13]
	v_mfma_f32_16x16x32_bf16 v[62:65], v[134:137], v[192:195], v[62:65]
	v_mfma_f32_16x16x32_bf16 v[58:61], v[154:157], v[192:195], v[58:61]
	v_mfma_f32_16x16x32_bf16 v[46:49], v[134:137], v[210:213], v[46:49]
	v_mfma_f32_16x16x32_bf16 v[42:45], v[154:157], v[210:213], v[42:45]
	v_mfma_f32_16x16x32_bf16 v[30:33], v[134:137], v[218:221], v[30:33]
	v_mfma_f32_16x16x32_bf16 v[26:29], v[154:157], v[218:221], v[26:29]
	v_mfma_f32_16x16x32_bf16 v[14:17], v[134:137], v[226:229], v[14:17]
	v_mfma_f32_16x16x32_bf16 v[10:13], v[154:157], v[226:229], v[10:13]
	v_mfma_f32_16x16x32_bf16 v[54:57], v[158:161], v[188:191], v[54:57]
	v_mfma_f32_16x16x32_bf16 v[50:53], v[180:183], v[188:191], v[50:53]
	v_mfma_f32_16x16x32_bf16 v[38:41], v[158:161], v[206:209], v[38:41]
	v_mfma_f32_16x16x32_bf16 v[34:37], v[180:183], v[206:209], v[34:37]
	v_mfma_f32_16x16x32_bf16 v[22:25], v[158:161], v[214:217], v[22:25]
	v_mfma_f32_16x16x32_bf16 v[18:21], v[180:183], v[214:217], v[18:21]
	v_mfma_f32_16x16x32_bf16 v[6:9], v[158:161], v[222:225], v[6:9]
	v_mfma_f32_16x16x32_bf16 v[2:5], v[180:183], v[222:225], v[2:5]
	v_mfma_f32_16x16x32_bf16 v[54:57], v[176:179], v[192:195], v[54:57]
	v_mfma_f32_16x16x32_bf16 v[50:53], v[184:187], v[192:195], v[50:53]
	v_mfma_f32_16x16x32_bf16 v[38:41], v[176:179], v[210:213], v[38:41]
	v_mfma_f32_16x16x32_bf16 v[34:37], v[184:187], v[210:213], v[34:37]
	v_mfma_f32_16x16x32_bf16 v[22:25], v[176:179], v[218:221], v[22:25]
	v_mfma_f32_16x16x32_bf16 v[18:21], v[184:187], v[218:221], v[18:21]
	v_mfma_f32_16x16x32_bf16 v[6:9], v[176:179], v[226:229], v[6:9]
	v_mfma_f32_16x16x32_bf16 v[2:5], v[184:187], v[226:229], v[2:5]
	s_barrier
	s_add_i32 s46, s46, 2
	s_add_u32 s18, s18, 0x100
	s_addc_u32 s19, s19, 0
	s_add_u32 s44, s44, 0x100
	s_addc_u32 s45, s45, 0
	s_cmp_gt_u32 s46, 29
	s_cbranch_scc0 .LBB0_440
	s_and_b64 vcc, exec, s[20:21]
	s_cbranch_vccz .LBB0_443
	s_barrier

.LBB0_1102:
	s_add_u32 s2, s22, 0xfff80080
	s_addc_u32 s20, s23, -1
	s_add_i32 s45, 0, 0x10000
	s_cmp_eq_u32 s44, 28
	s_cselect_b32 s25, s15, s20
	s_cselect_b32 s24, s40, s2
	s_cselect_b32 s21, s13, s43
	s_cselect_b32 s20, s41, s42
	s_add_u32 s100, s22, 0xfff80000
	s_addc_u32 s101, s23, -1
	s_add_i32 s2, 0, 0x14000
	v_add_u32_e32 v142, s45, v226
	v_add_u32_e32 v160, s2, v226
	s_mov_b32 m0, s38
	ds_read_b128 v[130:133], v142
	ds_read_b128 v[134:137], v142 offset:1024
	ds_read_b128 v[138:141], v142 offset:2048
	ds_read_b128 v[142:145], v142 offset:3072
	global_load_lds_dwordx4 v194, s[100:101]
	s_mov_b32 m0, s39
	ds_read_b128 v[148:151], v160
	ds_read_b128 v[152:155], v160 offset:1024
	ds_read_b128 v[156:159], v160 offset:2048
	ds_read_b128 v[160:163], v160 offset:3072
	global_load_lds_dwordx4 v206, s[100:101]
	s_add_i32 m0, s30, 0xc000
	ds_read_b128 v[164:167], v228
	ds_read_b128 v[168:171], v228 offset:1024
	ds_read_b128 v[172:175], v228 offset:2048
	ds_read_b128 v[176:179], v228 offset:3072
	global_load_lds_dwordx4 v194, s[22:23]
	s_add_i32 m0, s30, 0xe000
	ds_read_b128 v[180:183], v228 offset:4096
	ds_read_b128 v[184:187], v228 offset:5120
	ds_read_b128 v[208:211], v228 offset:6144
	ds_read_b128 v[212:215], v228 offset:7168
	global_load_lds_dwordx4 v206, s[22:23]
	s_waitcnt vmcnt(8)
	s_waitcnt lgkmcnt(0)
	s_barrier
	s_waitcnt lgkmcnt(0)
	v_mfma_f32_16x16x32_bf16 v[126:129], v[130:133], v[164:167], v[126:129]
	v_mfma_f32_16x16x32_bf16 v[122:125], v[138:141], v[164:167], v[122:125]
	v_mfma_f32_16x16x32_bf16 v[110:113], v[130:133], v[172:175], v[110:113]
	v_mfma_f32_16x16x32_bf16 v[106:109], v[138:141], v[172:175], v[106:109]
	v_mfma_f32_16x16x32_bf16 v[94:97], v[130:133], v[180:183], v[94:97]
	v_mfma_f32_16x16x32_bf16 v[90:93], v[138:141], v[180:183], v[90:93]
	v_mfma_f32_16x16x32_bf16 v[78:81], v[130:133], v[208:211], v[78:81]
	v_mfma_f32_16x16x32_bf16 v[74:77], v[138:141], v[208:211], v[74:77]
	v_mfma_f32_16x16x32_bf16 v[126:129], v[134:137], v[168:171], v[126:129]
	v_mfma_f32_16x16x32_bf16 v[122:125], v[142:145], v[168:171], v[122:125]
	v_mfma_f32_16x16x32_bf16 v[110:113], v[134:137], v[176:179], v[110:113]
	v_mfma_f32_16x16x32_bf16 v[106:109], v[142:145], v[176:179], v[106:109]
	v_mfma_f32_16x16x32_bf16 v[94:97], v[134:137], v[184:187], v[94:97]
	v_mfma_f32_16x16x32_bf16 v[90:93], v[142:145], v[184:187], v[90:93]
	v_mfma_f32_16x16x32_bf16 v[78:81], v[134:137], v[212:215], v[78:81]
	v_mfma_f32_16x16x32_bf16 v[74:77], v[142:145], v[212:215], v[74:77]
	v_mfma_f32_16x16x32_bf16 v[118:121], v[148:151], v[164:167], v[118:121]
	v_mfma_f32_16x16x32_bf16 v[114:117], v[156:159], v[164:167], v[114:117]
	v_mfma_f32_16x16x32_bf16 v[102:105], v[148:151], v[172:175], v[102:105]
	v_mfma_f32_16x16x32_bf16 v[98:101], v[156:159], v[172:175], v[98:101]
	v_mfma_f32_16x16x32_bf16 v[86:89], v[148:151], v[180:183], v[86:89]
	v_mfma_f32_16x16x32_bf16 v[82:85], v[156:159], v[180:183], v[82:85]
	v_mfma_f32_16x16x32_bf16 v[70:73], v[148:151], v[208:211], v[70:73]
	v_mfma_f32_16x16x32_bf16 v[66:69], v[156:159], v[208:211], v[66:69]
	v_mfma_f32_16x16x32_bf16 v[118:121], v[152:155], v[168:171], v[118:121]
	v_mfma_f32_16x16x32_bf16 v[114:117], v[160:163], v[168:171], v[114:117]
	v_mfma_f32_16x16x32_bf16 v[102:105], v[152:155], v[176:179], v[102:105]
	v_mfma_f32_16x16x32_bf16 v[98:101], v[160:163], v[176:179], v[98:101]
	v_mfma_f32_16x16x32_bf16 v[86:89], v[152:155], v[184:187], v[86:89]
	v_mfma_f32_16x16x32_bf16 v[82:85], v[160:163], v[184:187], v[82:85]
	v_mfma_f32_16x16x32_bf16 v[70:73], v[152:155], v[212:215], v[70:73]
	v_mfma_f32_16x16x32_bf16 v[66:69], v[160:163], v[212:215], v[66:69]
	s_barrier
	s_add_u32 s46, s20, 0x80000
	s_addc_u32 s47, s21, 0
	s_add_i32 s45, s45, s29
	s_mov_b32 m0, s45
	ds_read_b128 v[164:167], v228 offset:16384
	ds_read_b128 v[168:171], v228 offset:17408
	global_load_lds_dwordx4 v0, s[20:21]
	s_add_i32 m0, s45, 0x2000
	s_add_i32 s2, s2, s29
	ds_read_b128 v[172:175], v228 offset:18432
	ds_read_b128 v[176:179], v228 offset:19456
	global_load_lds_dwordx4 v188, s[20:21]
	s_mov_b32 m0, s2
	ds_read_b128 v[180:183], v228 offset:20480
	ds_read_b128 v[184:187], v228 offset:21504
	global_load_lds_dwordx4 v0, s[46:47]
	s_add_i32 m0, s2, 0x2000
	ds_read_b128 v[208:211], v228 offset:22528
	ds_read_b128 v[212:215], v228 offset:23552
	global_load_lds_dwordx4 v188, s[46:47]
	s_waitcnt vmcnt(6)
	s_waitcnt lgkmcnt(0)
	s_barrier
	s_waitcnt lgkmcnt(0)
	v_mfma_f32_16x16x32_bf16 v[62:65], v[130:133], v[164:167], v[62:65]
	v_mfma_f32_16x16x32_bf16 v[58:61], v[138:141], v[164:167], v[58:61]
	v_mfma_f32_16x16x32_bf16 v[46:49], v[130:133], v[172:175], v[46:49]
	v_mfma_f32_16x16x32_bf16 v[42:45], v[138:141], v[172:175], v[42:45]
	v_mfma_f32_16x16x32_bf16 v[30:33], v[130:133], v[180:183], v[30:33]
	v_mfma_f32_16x16x32_bf16 v[26:29], v[138:141], v[180:183], v[26:29]
	v_mfma_f32_16x16x32_bf16 v[14:17], v[130:133], v[208:211], v[14:17]
	v_mfma_f32_16x16x32_bf16 v[10:13], v[138:141], v[208:211], v[10:13]
	v_mfma_f32_16x16x32_bf16 v[62:65], v[134:137], v[168:171], v[62:65]
	v_mfma_f32_16x16x32_bf16 v[58:61], v[142:145], v[168:171], v[58:61]
	v_mfma_f32_16x16x32_bf16 v[46:49], v[134:137], v[176:179], v[46:49]
	v_mfma_f32_16x16x32_bf16 v[42:45], v[142:145], v[176:179], v[42:45]
	v_mfma_f32_16x16x32_bf16 v[30:33], v[134:137], v[184:187], v[30:33]
	v_mfma_f32_16x16x32_bf16 v[26:29], v[142:145], v[184:187], v[26:29]
	v_mfma_f32_16x16x32_bf16 v[14:17], v[134:137], v[212:215], v[14:17]
	v_mfma_f32_16x16x32_bf16 v[10:13], v[142:145], v[212:215], v[10:13]
	v_mfma_f32_16x16x32_bf16 v[54:57], v[148:151], v[164:167], v[54:57]
	v_mfma_f32_16x16x32_bf16 v[50:53], v[156:159], v[164:167], v[50:53]
	v_mfma_f32_16x16x32_bf16 v[38:41], v[148:151], v[172:175], v[38:41]
	v_mfma_f32_16x16x32_bf16 v[34:37], v[156:159], v[172:175], v[34:37]
	v_mfma_f32_16x16x32_bf16 v[22:25], v[148:151], v[180:183], v[22:25]
	v_mfma_f32_16x16x32_bf16 v[18:21], v[156:159], v[180:183], v[18:21]
	v_mfma_f32_16x16x32_bf16 v[6:9], v[148:151], v[208:211], v[6:9]
	v_mfma_f32_16x16x32_bf16 v[2:5], v[156:159], v[208:211], v[2:5]
	v_mfma_f32_16x16x32_bf16 v[54:57], v[152:155], v[168:171], v[54:57]
	v_mfma_f32_16x16x32_bf16 v[50:53], v[160:163], v[168:171], v[50:53]
	v_mfma_f32_16x16x32_bf16 v[38:41], v[152:155], v[176:179], v[38:41]
	v_mfma_f32_16x16x32_bf16 v[34:37], v[160:163], v[176:179], v[34:37]
	v_mfma_f32_16x16x32_bf16 v[22:25], v[152:155], v[184:187], v[22:25]
	v_mfma_f32_16x16x32_bf16 v[18:21], v[160:163], v[184:187], v[18:21]
	v_mfma_f32_16x16x32_bf16 v[6:9], v[152:155], v[212:215], v[6:9]
	v_mfma_f32_16x16x32_bf16 v[2:5], v[160:163], v[212:215], v[2:5]
	s_barrier
	s_add_u32 s24, s24, 0x80000
	s_addc_u32 s25, s25, 0
	s_add_u32 s100, s24, 0xfff80000
	s_addc_u32 s101, s25, -1
	s_add_i32 s2, 0, 0x18000
	s_add_i32 s45, 0, 0x1c000
	v_add_u32_e32 v142, s2, v226
	v_add_u32_e32 v160, s45, v226
	s_mov_b32 m0, s30
	ds_read_b128 v[130:133], v142
	ds_read_b128 v[134:137], v142 offset:1024
	ds_read_b128 v[138:141], v142 offset:2048
	ds_read_b128 v[142:145], v142 offset:3072
	global_load_lds_dwordx4 v192, s[100:101]
	s_mov_b32 m0, s31
	ds_read_b128 v[148:151], v160
	ds_read_b128 v[152:155], v160 offset:1024
	ds_read_b128 v[156:159], v160 offset:2048
	ds_read_b128 v[160:163], v160 offset:3072
	global_load_lds_dwordx4 v190, s[100:101]
	s_mov_b32 m0, s35
	ds_read_b128 v[164:167], v228 offset:32768
	ds_read_b128 v[168:171], v228 offset:33792
	ds_read_b128 v[172:175], v228 offset:34816
	ds_read_b128 v[176:179], v228 offset:35840
	global_load_lds_dwordx4 v192, s[24:25]
	s_mov_b32 m0, s36
	ds_read_b128 v[180:183], v228 offset:36864
	ds_read_b128 v[184:187], v228 offset:37888
	ds_read_b128 v[208:211], v228 offset:38912
	ds_read_b128 v[212:215], v228 offset:39936
	global_load_lds_dwordx4 v190, s[24:25]
	s_waitcnt vmcnt(8)
	s_waitcnt lgkmcnt(0)
	s_barrier
	s_waitcnt lgkmcnt(0)
	v_mfma_f32_16x16x32_bf16 v[126:129], v[130:133], v[164:167], v[126:129]
	v_mfma_f32_16x16x32_bf16 v[122:125], v[138:141], v[164:167], v[122:125]
	v_mfma_f32_16x16x32_bf16 v[110:113], v[130:133], v[172:175], v[110:113]
	v_mfma_f32_16x16x32_bf16 v[106:109], v[138:141], v[172:175], v[106:109]
	v_mfma_f32_16x16x32_bf16 v[94:97], v[130:133], v[180:183], v[94:97]
	v_mfma_f32_16x16x32_bf16 v[90:93], v[138:141], v[180:183], v[90:93]
	v_mfma_f32_16x16x32_bf16 v[78:81], v[130:133], v[208:211], v[78:81]
	v_mfma_f32_16x16x32_bf16 v[74:77], v[138:141], v[208:211], v[74:77]
	v_mfma_f32_16x16x32_bf16 v[126:129], v[134:137], v[168:171], v[126:129]
	v_mfma_f32_16x16x32_bf16 v[122:125], v[142:145], v[168:171], v[122:125]
	v_mfma_f32_16x16x32_bf16 v[110:113], v[134:137], v[176:179], v[110:113]
	v_mfma_f32_16x16x32_bf16 v[106:109], v[142:145], v[176:179], v[106:109]
	v_mfma_f32_16x16x32_bf16 v[94:97], v[134:137], v[184:187], v[94:97]
	v_mfma_f32_16x16x32_bf16 v[90:93], v[142:145], v[184:187], v[90:93]
	v_mfma_f32_16x16x32_bf16 v[78:81], v[134:137], v[212:215], v[78:81]
	v_mfma_f32_16x16x32_bf16 v[74:77], v[142:145], v[212:215], v[74:77]
	v_mfma_f32_16x16x32_bf16 v[118:121], v[148:151], v[164:167], v[118:121]
	v_mfma_f32_16x16x32_bf16 v[114:117], v[156:159], v[164:167], v[114:117]
	v_mfma_f32_16x16x32_bf16 v[102:105], v[148:151], v[172:175], v[102:105]
	v_mfma_f32_16x16x32_bf16 v[98:101], v[156:159], v[172:175], v[98:101]
	v_mfma_f32_16x16x32_bf16 v[86:89], v[148:151], v[180:183], v[86:89]
	v_mfma_f32_16x16x32_bf16 v[82:85], v[156:159], v[180:183], v[82:85]
	v_mfma_f32_16x16x32_bf16 v[70:73], v[148:151], v[208:211], v[70:73]
	v_mfma_f32_16x16x32_bf16 v[66:69], v[156:159], v[208:211], v[66:69]
	v_mfma_f32_16x16x32_bf16 v[118:121], v[152:155], v[168:171], v[118:121]
	v_mfma_f32_16x16x32_bf16 v[114:117], v[160:163], v[168:171], v[114:117]
	v_mfma_f32_16x16x32_bf16 v[102:105], v[152:155], v[176:179], v[102:105]
	v_mfma_f32_16x16x32_bf16 v[98:101], v[160:163], v[176:179], v[98:101]
	v_mfma_f32_16x16x32_bf16 v[86:89], v[152:155], v[184:187], v[86:89]
	v_mfma_f32_16x16x32_bf16 v[82:85], v[160:163], v[184:187], v[82:85]
	v_mfma_f32_16x16x32_bf16 v[70:73], v[152:155], v[212:215], v[70:73]
	v_mfma_f32_16x16x32_bf16 v[66:69], v[160:163], v[212:215], v[66:69]
	s_barrier
	s_add_u32 s20, s20, 0x80080
	s_addc_u32 s21, s21, 0
	s_add_u32 s46, s46, 0xfff80080
	s_addc_u32 s47, s47, -1
	s_add_i32 s2, s2, s29
	s_mov_b32 m0, s2
	ds_read_b128 v[164:167], v228 offset:49152
	ds_read_b128 v[168:171], v228 offset:50176
	global_load_lds_dwordx4 v0, s[46:47]
	s_add_i32 m0, s2, 0x2000
	s_add_i32 s2, s45, s29
	ds_read_b128 v[172:175], v228 offset:51200
	ds_read_b128 v[176:179], v228 offset:52224
	global_load_lds_dwordx4 v188, s[46:47]
	s_mov_b32 m0, s2
	ds_read_b128 v[180:183], v228 offset:53248
	ds_read_b128 v[184:187], v228 offset:54272
	global_load_lds_dwordx4 v0, s[20:21]
	s_add_i32 m0, s2, 0x2000
	ds_read_b128 v[208:211], v228 offset:55296
	ds_read_b128 v[212:215], v228 offset:56320
	global_load_lds_dwordx4 v188, s[20:21]
	s_waitcnt vmcnt(6)
	s_waitcnt lgkmcnt(0)
	s_barrier
	s_waitcnt lgkmcnt(0)
	v_mfma_f32_16x16x32_bf16 v[62:65], v[130:133], v[164:167], v[62:65]
	v_mfma_f32_16x16x32_bf16 v[58:61], v[138:141], v[164:167], v[58:61]
	v_mfma_f32_16x16x32_bf16 v[46:49], v[130:133], v[172:175], v[46:49]
	v_mfma_f32_16x16x32_bf16 v[42:45], v[138:141], v[172:175], v[42:45]
	v_mfma_f32_16x16x32_bf16 v[30:33], v[130:133], v[180:183], v[30:33]
	v_mfma_f32_16x16x32_bf16 v[26:29], v[138:141], v[180:183], v[26:29]
	v_mfma_f32_16x16x32_bf16 v[14:17], v[130:133], v[208:211], v[14:17]
	v_mfma_f32_16x16x32_bf16 v[10:13], v[138:141], v[208:211], v[10:13]
	v_mfma_f32_16x16x32_bf16 v[62:65], v[134:137], v[168:171], v[62:65]
	v_mfma_f32_16x16x32_bf16 v[58:61], v[142:145], v[168:171], v[58:61]
	v_mfma_f32_16x16x32_bf16 v[46:49], v[134:137], v[176:179], v[46:49]
	v_mfma_f32_16x16x32_bf16 v[42:45], v[142:145], v[176:179], v[42:45]
	v_mfma_f32_16x16x32_bf16 v[30:33], v[134:137], v[184:187], v[30:33]
	v_mfma_f32_16x16x32_bf16 v[26:29], v[142:145], v[184:187], v[26:29]
	v_mfma_f32_16x16x32_bf16 v[14:17], v[134:137], v[212:215], v[14:17]
	v_mfma_f32_16x16x32_bf16 v[10:13], v[142:145], v[212:215], v[10:13]
	v_mfma_f32_16x16x32_bf16 v[54:57], v[148:151], v[164:167], v[54:57]
	v_mfma_f32_16x16x32_bf16 v[50:53], v[156:159], v[164:167], v[50:53]
	v_mfma_f32_16x16x32_bf16 v[38:41], v[148:151], v[172:175], v[38:41]
	v_mfma_f32_16x16x32_bf16 v[34:37], v[156:159], v[172:175], v[34:37]
	v_mfma_f32_16x16x32_bf16 v[22:25], v[148:151], v[180:183], v[22:25]
	v_mfma_f32_16x16x32_bf16 v[18:21], v[156:159], v[180:183], v[18:21]
	v_mfma_f32_16x16x32_bf16 v[6:9], v[148:151], v[208:211], v[6:9]
	v_mfma_f32_16x16x32_bf16 v[2:5], v[156:159], v[208:211], v[2:5]
	v_mfma_f32_16x16x32_bf16 v[54:57], v[152:155], v[168:171], v[54:57]
	v_mfma_f32_16x16x32_bf16 v[50:53], v[160:163], v[168:171], v[50:53]
	v_mfma_f32_16x16x32_bf16 v[38:41], v[152:155], v[176:179], v[38:41]
	v_mfma_f32_16x16x32_bf16 v[34:37], v[160:163], v[176:179], v[34:37]
	v_mfma_f32_16x16x32_bf16 v[22:25], v[152:155], v[184:187], v[22:25]
	v_mfma_f32_16x16x32_bf16 v[18:21], v[160:163], v[184:187], v[18:21]
	v_mfma_f32_16x16x32_bf16 v[6:9], v[152:155], v[212:215], v[6:9]
	v_mfma_f32_16x16x32_bf16 v[2:5], v[160:163], v[212:215], v[2:5]
	s_barrier
	s_add_i32 s44, s44, 2
	s_add_u32 s22, s22, 0x100
	s_addc_u32 s23, s23, 0
	s_add_u32 s42, s42, 0x100
	s_addc_u32 s43, s43, 0
	s_cmp_gt_u32 s44, 29
	s_cbranch_scc0 .LBB0_1102
	v_lshl_or_b32 v210, s3, 8, v227
	v_lshl_add_u32 v224, s34, 8, v147
	v_ashrrev_i32_e32 v211, 31, v210
	v_lshlrev_b64 v[130:131], 1, v[210:211]
	v_ashrrev_i32_e32 v225, 31, v224
	v_lshl_add_u64 v[132:133], s[8:9], 0, v[130:131]
	v_lshlrev_b64 v[134:135], 12, v[224:225]
	v_lshl_add_u64 v[136:137], v[132:133], 0, v[134:135]
	global_load_dwordx4 v[240:243], v[136:137], off
	global_load_dwordx4 v[244:247], v[136:137], off offset:256
	v_or_b32_e32 v222, 16, v224
	v_or_b32_e32 v220, 32, v224
	v_or_b32_e32 v218, 48, v224
	v_add_u32_e32 v216, 0x80, v224
	v_add_u32_e32 v214, 0x90, v224
	v_add_u32_e32 v212, 0xa0, v224
	v_add_u32_e32 v208, 0xb0, v224
	v_ashrrev_i32_e32 v223, 31, v222
	v_ashrrev_i32_e32 v221, 31, v220
	v_ashrrev_i32_e32 v219, 31, v218
	v_ashrrev_i32_e32 v217, 31, v216
	v_ashrrev_i32_e32 v215, 31, v214
	v_ashrrev_i32_e32 v213, 31, v212
	v_ashrrev_i32_e32 v209, 31, v208
	v_lshlrev_b64 v[136:137], 12, v[222:223]
	v_lshlrev_b64 v[138:139], 12, v[220:221]
	v_lshlrev_b64 v[140:141], 12, v[218:219]
	v_lshlrev_b64 v[142:143], 12, v[216:217]
	v_lshlrev_b64 v[144:145], 12, v[214:215]
	v_lshlrev_b64 v[148:149], 12, v[212:213]
	v_lshlrev_b64 v[150:151], 12, v[208:209]
	v_lshl_add_u64 v[134:135], s[8:9], 0, v[134:135]
	v_lshl_add_u64 v[136:137], v[132:133], 0, v[136:137]
	v_lshl_add_u64 v[138:139], v[132:133], 0, v[138:139]
	v_lshl_add_u64 v[140:141], v[132:133], 0, v[140:141]
	v_lshl_add_u64 v[142:143], v[132:133], 0, v[142:143]
	v_lshl_add_u64 v[144:145], v[132:133], 0, v[144:145]
	v_lshl_add_u64 v[236:237], v[132:133], 0, v[148:149]
	v_lshl_add_u64 v[132:133], v[132:133], 0, v[150:151]
	v_lshl_add_u64 v[248:249], v[134:135], 0, v[130:131]
	global_load_dwordx4 v[184:187], v[136:137], off
	global_load_dwordx4 v[180:183], v[136:137], off offset:256
	global_load_dwordx4 v[176:179], v[138:139], off
	global_load_dwordx4 v[172:175], v[138:139], off offset:256
	global_load_dwordx4 v[168:171], v[140:141], off
	global_load_dwordx4 v[164:167], v[140:141], off offset:256
	global_load_dwordx4 v[160:163], v[142:143], off
	global_load_dwordx4 v[156:159], v[142:143], off offset:256
	global_load_dwordx4 v[152:155], v[144:145], off
	global_load_dwordx4 v[148:151], v[144:145], off offset:256
	s_nop 0
	global_load_dwordx4 v[142:145], v[236:237], off
	global_load_dwordx4 v[138:141], v[236:237], off offset:256
	global_load_dwordx4 v[134:137], v[132:133], off
	s_nop 0
	global_load_dwordx4 v[130:133], v[132:133], off offset:256
	s_lshl_b32 s20, s3, 2
	s_ashr_i32 s21, s20, 31
	s_waitcnt vmcnt(0)
	v_lshlrev_b32_e32 v236, 16, v240
	v_and_b32_e32 v237, 0xffff0000, v240
	v_lshlrev_b32_e32 v250, 16, v242
	v_and_b32_e32 v251, 0xffff0000, v242
	v_lshlrev_b32_e32 v242, 16, v243
	v_and_b32_e32 v243, 0xffff0000, v243
	v_lshlrev_b32_e32 v240, 16, v241
	v_and_b32_e32 v241, 0xffff0000, v241
	v_pk_add_f32 v[126:127], v[126:127], v[236:237]
	v_pk_add_f32 v[236:237], v[124:125], v[242:243]
	v_pk_add_f32 v[124:125], v[122:123], v[250:251]
	v_pk_add_f32 v[128:129], v[128:129], v[240:241]
	v_cvt_pk_bf16_f32 v122, v126, v127
	v_lshlrev_b32_e32 v252, 16, v244
	v_cvt_pk_bf16_f32 v123, v128, v129
	v_cvt_pk_bf16_f32 v124, v124, v125
	v_cvt_pk_bf16_f32 v125, v236, v237
	global_store_dwordx4 v[248:249], v[122:125], off
	v_lshlrev_b32_e32 v126, 16, v122
	v_lshlrev_b32_e32 v127, 16, v123
	v_and_b32_e32 v122, 0xffff0000, v122
	v_and_b32_e32 v123, 0xffff0000, v123
	v_lshlrev_b32_e32 v128, 16, v124
	v_and_b32_e32 v124, 0xffff0000, v124
	v_lshlrev_b32_e32 v129, 16, v125
	v_and_b32_e32 v125, 0xffff0000, v125
	v_mul_f32_e32 v122, v122, v122
	v_mul_f32_e32 v123, v123, v123
	v_mul_f32_e32 v124, v124, v124
	v_mul_f32_e32 v125, v125, v125
	v_fmac_f32_e32 v122, v126, v126
	v_fmac_f32_e32 v123, v127, v127
	v_fmac_f32_e32 v124, v128, v128
	v_fmac_f32_e32 v125, v129, v129
	v_add_f32_e32 v122, v122, v123
	v_add_f32_e32 v123, v124, v125
	v_and_b32_e32 v253, 0xffff0000, v244
	v_add_f32_e32 v128, v122, v123
	v_lshlrev_b32_e32 v122, 16, v245
	v_and_b32_e32 v123, 0xffff0000, v245
	v_lshlrev_b32_e32 v124, 16, v246
	v_and_b32_e32 v125, 0xffff0000, v246
	v_lshlrev_b32_e32 v126, 16, v247
	v_and_b32_e32 v127, 0xffff0000, v247
	v_pk_add_f32 v[120:121], v[120:121], v[122:123]
	v_pk_add_f32 v[118:119], v[118:119], v[252:253]
	v_pk_add_f32 v[122:123], v[116:117], v[126:127]
	v_pk_add_f32 v[116:117], v[114:115], v[124:125]
	v_cvt_pk_bf16_f32 v114, v118, v119
	v_cvt_pk_bf16_f32 v115, v120, v121
	s_nop 0
	v_cvt_pk_bf16_f32 v116, v116, v117
	v_cvt_pk_bf16_f32 v117, v122, v123
	global_store_dwordx4 v[248:249], v[114:117], off offset:256
	v_lshlrev_b32_e32 v118, 16, v114
	v_lshlrev_b32_e32 v119, 16, v115
	v_and_b32_e32 v114, 0xffff0000, v114
	v_and_b32_e32 v115, 0xffff0000, v115
	v_mul_f32_e32 v114, v114, v114
	v_mul_f32_e32 v115, v115, v115
	v_lshlrev_b32_e32 v120, 16, v116
	v_and_b32_e32 v116, 0xffff0000, v116
	v_lshlrev_b32_e32 v121, 16, v117
	v_and_b32_e32 v117, 0xffff0000, v117
	v_fmac_f32_e32 v114, v118, v118
	v_fmac_f32_e32 v115, v119, v119
	v_add_f32_e32 v114, v114, v115
	v_mul_f32_e32 v115, v116, v116
	v_mul_f32_e32 v116, v117, v117
	v_fmac_f32_e32 v115, v120, v120
	v_fmac_f32_e32 v116, v121, v121
	v_add_f32_e32 v115, v115, v116
	v_add_f32_e32 v114, v114, v115
	s_mov_b32 s2, 0
	v_add_f32_e32 v114, v128, v114
	v_mbcnt_lo_u32_b32 v115, -1, s2
	v_mbcnt_hi_u32_b32 v115, -1, v115
	v_lshlrev_b32_e32 v115, 2, v115
	v_xor_b32_e32 v115, 64, v115
	ds_bpermute_b32 v115, v115, v114
	s_mov_b32 s2, 0
	s_waitcnt lgkmcnt(0)
	v_add_f32_e32 v114, v114, v115
	v_mbcnt_lo_u32_b32 v115, -1, s2
	v_mbcnt_hi_u32_b32 v115, -1, v115
	v_lshlrev_b32_e32 v115, 2, v115
	v_xor_b32_e32 v115, 0x80, v115
	ds_bpermute_b32 v115, v115, v114
	s_and_saveexec_b64 s[22:23], s[4:5]
	s_cbranch_execz .LBB0_1105
	v_lshlrev_b64 v[116:117], 7, v[224:225]
	v_lshl_add_u64 v[116:117], s[10:11], 0, v[116:117]
	v_lshl_add_u64 v[116:117], s[20:21], 2, v[116:117]
	s_lshl_b32 s50, s37, 2
	v_lshl_add_u64 v[116:117], v[116:117], 0, s[50:51]
	s_waitcnt lgkmcnt(0)
	v_add_f32_e32 v114, v114, v115
	global_store_dword v[116:117], v114, off
